# HGRN: producer loads via scalar base, steady-state vmcnt, L2 prefetch by consumer waves; q/k prep loop software-pipelined 2 deep
# speedup vs baseline: 1.0109x; 1.0028x over previous
.LBB0_75:
	s_cmp_lg_u32 s96, 1
	s_cselect_b64 s[0:1], -1, 0
	v_writelane_b32 v246, s0, 0
	s_and_b64 vcc, exec, s[0:1]
	s_nop 0
	v_writelane_b32 v246, s1, 1
	s_cbranch_vccnz .LBB0_342
	v_readlane_b32 s10, v249, 37
	v_readlane_b32 s11, v249, 38
	s_mov_b64 s[0:1], -1
	s_and_b64 vcc, exec, s[10:11]
	v_readlane_b32 s4, v247, 55
	v_readlane_b32 s14, v247, 59
	v_readlane_b32 s15, v247, 56
	v_readlane_b32 s16, v247, 60
	s_mov_b32 s17, 0x66666667
	s_movk_i32 s18, 0xffec
	s_movk_i32 s23, 0xf600
	s_cbranch_vccz .LBB0_108
	v_mov_b32_e32 v16, v188
	s_nop 0
	v_readfirstlane_b32 s0, v16
	s_ashr_i32 s0, s0, 6
	s_add_i32 s3, s0, s52
	s_cmp_gt_i32 s3, 0x13fff
	s_cbranch_scc1 .LBB0_84
	v_and_b32_e32 v19, 7, v16
	v_bfe_u32 v17, v16, 3, 1
	v_lshlrev_b32_e32 v0, 2, v19
	v_lshl_or_b32 v18, v17, 6, v0
	v_readlane_b32 s60, v249, 0
	v_lshlrev_b32_e32 v12, 2, v18
	v_readlane_b32 s68, v249, 8
	v_readlane_b32 s69, v249, 9
	v_readlane_b32 s70, v249, 10
	v_readlane_b32 s71, v249, 11
	s_waitcnt lgkmcnt(0)
	s_nop 1
	global_load_dwordx4 v[0:3], v12, s[68:69]
	s_nop 0
	global_load_dwordx4 v[4:7], v12, s[70:71]
	global_load_dwordx4 v[8:11], v12, s[68:69] offset:128
	s_lshl_b32 s0, s0, 2
	global_load_dwordx4 v[12:15], v12, s[70:71] offset:128
	v_readlane_b32 s1, v247, 57
	v_readlane_b32 s61, v249, 1
	v_readlane_b32 s62, v249, 2
	v_readlane_b32 s63, v249, 3
	v_readlane_b32 s64, v249, 4
	v_readlane_b32 s65, v249, 5
	v_bfe_u32 v16, v16, 4, 2
	s_add_i32 s0, s1, s0
	v_readlane_b32 s67, v249, 7
	v_readlane_b32 s72, v249, 12
	v_readlane_b32 s73, v249, 13
	v_readlane_b32 s64, v248, 14
	v_readlane_b32 s62, v248, 12
	v_readlane_b32 s60, v248, 9
	v_readlane_b32 s68, v248, 16
	v_readlane_b32 s70, v248, 18
	v_cmp_eq_u32_e32 vcc, 0, v17
	v_lshlrev_b32_e32 v17, 1, v19
	v_add_u32_e32 v24, s0, v16
	v_readlane_b32 s67, v248, 23
	v_readlane_b32 s65, v248, 15
	v_readlane_b32 s63, v248, 13
	v_readlane_b32 s73, v248, 25
	v_readlane_b32 s72, v248, 24
	v_readlane_b32 s61, v248, 10
	v_readlane_b32 s69, v248, 17
	v_readlane_b32 s71, v248, 19
	v_lshlrev_b32_e32 v26, 7, v24
	v_lshlrev_b32_e32 v28, 1, v18
	v_mov_b32_e32 v29, v97
	v_lshlrev_b32_e32 v25, 4, v17
	v_readlane_b32 s66, v249, 6
	v_readlane_b32 s74, v249, 14
	v_readlane_b32 s75, v249, 15
	s_waitcnt vmcnt(0)
	v_mul_hi_i32 v16, v24, s17
	v_lshrrev_b32_e32 v17, 31, v16
	v_ashrrev_i32_e32 v16, 3, v16
	v_add_u32_e32 v30, v16, v17
	v_mad_u64_u32 v[16:17], s[0:1], v30, s18, v[24:25]
	v_cmp_lt_i32_e64 s[0:1], 15, v16
	v_ashrrev_i32_e32 v31, 31, v30
	v_mad_u64_u32 v[34:35], s[10:11], v30, s23, v[26:27]
	s_and_saveexec_b64 s[10:11], s[0:1]
	s_xor_b64 s[0:1], exec, s[10:11]
	v_lshlrev_b64 v[16:17], 10, v[30:31]
	v_lshl_add_u64 v[16:17], s[50:51], 0, v[16:17]
	v_add_u32_e32 v96, 0xfffff800, v34
	v_lshl_add_u64 v[32:33], v[96:97], 1, v[16:17]
	s_or_saveexec_b64 s[0:1], s[0:1]
	v_mov_b64_e32 v[18:19], v[14:15]
	v_mov_b64_e32 v[22:23], v[6:7]
	v_mov_b64_e32 v[16:17], v[12:13]
	v_mov_b64_e32 v[20:21], v[4:5]
	s_xor_b64 exec, exec, s[0:1]
	s_cbranch_execz .Lpp_join_1
	v_lshlrev_b64 v[16:17], 12, v[30:31]
	v_lshl_add_u64 v[16:17], s[48:49], 0, v[16:17]
	v_ashrrev_i32_e32 v35, 31, v34
	v_lshl_add_u64 v[32:33], v[34:35], 1, v[16:17]
	v_mov_b64_e32 v[18:19], v[10:11]
	v_mov_b64_e32 v[22:23], v[2:3]
	v_mov_b64_e32 v[16:17], v[8:9]
	v_mov_b64_e32 v[20:21], v[0:1]
.Lpp_join_1:
	s_or_b64 exec, exec, s[0:1]
	v_lshl_add_u64 v[38:39], v[32:33], 0, v[28:29]
	global_load_dwordx2 v[40:41], v[38:39], off
	global_load_dwordx2 v[42:43], v[38:39], off offset:64
	v_and_b32_e32 v27, 63, v30
	v_bfe_u32 v30, v30, 6, 7
	v_cndmask_b32_e32 v27, v27, v30, vcc
	v_lshl_or_b32 v27, v27, 8, v25
	global_load_dwordx4 v[30:33], v27, s[24:25]
	global_load_dwordx4 v[34:37], v27, s[24:25] offset:16
	s_add_i32 s3, s3, s56
	v_add_u32_e32 v26, s4, v26
	v_add_u32_e32 v24, s14, v24
	s_cmp_lt_i32 s3, 0x14000
	s_cbranch_scc0 .Lpp_tailA
	v_mul_hi_i32 v60, v24, s17
	v_lshrrev_b32_e32 v61, 31, v60
	v_ashrrev_i32_e32 v60, 3, v60
	v_add_u32_e32 v70, v60, v61
	v_mad_u64_u32 v[60:61], s[0:1], v70, s18, v[24:25]
	v_cmp_lt_i32_e64 s[0:1], 15, v60
	v_ashrrev_i32_e32 v71, 31, v70
	v_mad_u64_u32 v[74:75], s[10:11], v70, s23, v[26:27]
	s_and_saveexec_b64 s[10:11], s[0:1]
	s_xor_b64 s[0:1], exec, s[10:11]
	v_lshlrev_b64 v[60:61], 10, v[70:71]
	v_lshl_add_u64 v[60:61], s[50:51], 0, v[60:61]
	v_add_u32_e32 v96, 0xfffff800, v74
	v_lshl_add_u64 v[72:73], v[96:97], 1, v[60:61]
	s_or_saveexec_b64 s[0:1], s[0:1]
	v_mov_b64_e32 v[62:63], v[14:15]
	v_mov_b64_e32 v[66:67], v[6:7]
	v_mov_b64_e32 v[60:61], v[12:13]
	v_mov_b64_e32 v[64:65], v[4:5]
	s_xor_b64 exec, exec, s[0:1]
	s_cbranch_execz .Lpp_join_2
	v_lshlrev_b64 v[60:61], 12, v[70:71]
	v_lshl_add_u64 v[60:61], s[48:49], 0, v[60:61]
	v_ashrrev_i32_e32 v75, 31, v74
	v_lshl_add_u64 v[72:73], v[74:75], 1, v[60:61]
	v_mov_b64_e32 v[62:63], v[10:11]
	v_mov_b64_e32 v[66:67], v[2:3]
	v_mov_b64_e32 v[60:61], v[8:9]
	v_mov_b64_e32 v[64:65], v[0:1]
.Lpp_join_2:
	s_or_b64 exec, exec, s[0:1]
	v_lshl_add_u64 v[78:79], v[72:73], 0, v[28:29]
	global_load_dwordx2 v[80:81], v[78:79], off
	global_load_dwordx2 v[82:83], v[78:79], off offset:64
	v_and_b32_e32 v27, 63, v70
	v_bfe_u32 v70, v70, 6, 7
	v_cndmask_b32_e32 v27, v27, v70, vcc
	v_lshl_or_b32 v27, v27, 8, v25
	global_load_dwordx4 v[70:73], v27, s[24:25]
	global_load_dwordx4 v[74:77], v27, s[24:25] offset:16
	s_add_i32 s3, s3, s56
	v_add_u32_e32 v26, s4, v26
	v_add_u32_e32 v24, s14, v24
	s_waitcnt vmcnt(4)
	v_lshlrev_b32_e32 v44, 16, v41
	v_and_b32_e32 v45, 0xffff0000, v41
	v_lshlrev_b32_e32 v48, 16, v40
	v_and_b32_e32 v49, 0xffff0000, v40
	v_lshlrev_b32_e32 v40, 16, v42
	v_and_b32_e32 v41, 0xffff0000, v42
	v_lshlrev_b32_e32 v46, 16, v43
	v_and_b32_e32 v47, 0xffff0000, v43
	v_pk_mul_f32 v[50:51], v[40:41], v[40:41]
	v_pk_mul_f32 v[42:43], v[46:47], v[46:47]
	v_pk_fma_f32 v[50:51], v[48:49], v[48:49], v[50:51]
	v_pk_fma_f32 v[42:43], v[44:45], v[44:45], v[42:43]
	v_add_f32_e32 v27, v50, v51
	v_add_f32_e32 v27, v42, v27
	v_add_f32_e32 v27, v43, v27
	v_mov_b32_e32 v52, v31
	v_mov_b32_e32 v31, v32
	v_add_f32_dpp v27, v27, v27 quad_perm:[1,0,3,2] row_mask:0xf bank_mask:0xf bound_ctrl:1
	v_mov_b32_e32 v53, v33
	v_mov_b32_e32 v33, v37
	v_add_f32_dpp v27, v27, v27 quad_perm:[2,3,0,1] row_mask:0xf bank_mask:0xf bound_ctrl:1
	s_nop 1
	v_add_f32_dpp v27, v27, v27 row_half_mirror row_mask:0xf bank_mask:0xf bound_ctrl:1
	s_nop 1
	v_add_f32_dpp v27, v27, v27 row_mirror row_mask:0xf bank_mask:0xf bound_ctrl:1
	v_fmamk_f32 v27, v27, 0x3c000000, v189
	v_mul_f32_e32 v32, 0x4b800000, v27
	v_cmp_gt_f32_e64 s[0:1], s2, v27
	s_nop 1
	v_cndmask_b32_e64 v27, v27, v32, s[0:1]
	v_rsq_f32_e32 v27, v27
	v_mov_b32_e32 v32, v35
	v_mov_b32_e32 v35, v36
	v_mul_f32_e32 v36, 0x45800000, v27
	v_cndmask_b32_e64 v36, v27, v36, s[0:1]
	v_pk_mul_f32 v[42:43], v[36:37], v[48:49] op_sel_hi:[0,1]
	v_pk_mul_f32 v[40:41], v[36:37], v[40:41] op_sel_hi:[0,1]
	v_pk_mul_f32 v[44:45], v[36:37], v[44:45] op_sel_hi:[0,1]
	v_pk_mul_f32 v[36:37], v[36:37], v[46:47] op_sel_hi:[0,1]
	v_pk_mul_f32 v[16:17], v[16:17], v[40:41]
	v_pk_mul_f32 v[18:19], v[18:19], v[36:37]
	v_pk_mul_f32 v[20:21], v[20:21], v[42:43]
	v_pk_mul_f32 v[22:23], v[22:23], v[44:45]
	v_pk_mul_f32 v[36:37], v[30:31], v[16:17]
	v_pk_mul_f32 v[16:17], v[52:53], v[16:17]
	v_pk_mul_f32 v[40:41], v[34:35], v[18:19]
	v_pk_mul_f32 v[18:19], v[32:33], v[18:19]
	v_pk_fma_f32 v[16:17], v[30:31], v[20:21], v[16:17] neg_lo:[0,0,1] neg_hi:[0,0,1]
	v_pk_fma_f32 v[18:19], v[34:35], v[22:23], v[18:19] neg_lo:[0,0,1] neg_hi:[0,0,1]
	v_pk_fma_f32 v[36:37], v[52:53], v[20:21], v[36:37]
	v_pk_fma_f32 v[20:21], v[32:33], v[22:23], v[40:41]
	v_cvt_pk_bf16_f32 v16, v16, v17
	v_cvt_pk_bf16_f32 v17, v18, v19
	v_cvt_pk_bf16_f32 v18, v36, v37
	v_cvt_pk_bf16_f32 v19, v20, v21
	global_store_dwordx2 v[38:39], v[16:17], off
	global_store_dwordx2 v[38:39], v[18:19], off offset:64
.Lpp_loop:
	s_cmp_lt_i32 s3, 0x14000
	s_cbranch_scc0 .Lpp_tailB
	v_mul_hi_i32 v16, v24, s17
	v_lshrrev_b32_e32 v17, 31, v16
	v_ashrrev_i32_e32 v16, 3, v16
	v_add_u32_e32 v30, v16, v17
	v_mad_u64_u32 v[16:17], s[0:1], v30, s18, v[24:25]
	v_cmp_lt_i32_e64 s[0:1], 15, v16
	v_ashrrev_i32_e32 v31, 31, v30
	v_mad_u64_u32 v[34:35], s[10:11], v30, s23, v[26:27]
	s_and_saveexec_b64 s[10:11], s[0:1]
	s_xor_b64 s[0:1], exec, s[10:11]
	v_lshlrev_b64 v[16:17], 10, v[30:31]
	v_lshl_add_u64 v[16:17], s[50:51], 0, v[16:17]
	v_add_u32_e32 v96, 0xfffff800, v34
	v_lshl_add_u64 v[32:33], v[96:97], 1, v[16:17]
	s_or_saveexec_b64 s[0:1], s[0:1]
	v_mov_b64_e32 v[18:19], v[14:15]
	v_mov_b64_e32 v[22:23], v[6:7]
	v_mov_b64_e32 v[16:17], v[12:13]
	v_mov_b64_e32 v[20:21], v[4:5]
	s_xor_b64 exec, exec, s[0:1]
	s_cbranch_execz .Lpp_join_3
	v_lshlrev_b64 v[16:17], 12, v[30:31]
	v_lshl_add_u64 v[16:17], s[48:49], 0, v[16:17]
	v_ashrrev_i32_e32 v35, 31, v34
	v_lshl_add_u64 v[32:33], v[34:35], 1, v[16:17]
	v_mov_b64_e32 v[18:19], v[10:11]
	v_mov_b64_e32 v[22:23], v[2:3]
	v_mov_b64_e32 v[16:17], v[8:9]
	v_mov_b64_e32 v[20:21], v[0:1]
.Lpp_join_3:
	s_or_b64 exec, exec, s[0:1]
	v_lshl_add_u64 v[38:39], v[32:33], 0, v[28:29]
	global_load_dwordx2 v[40:41], v[38:39], off
	global_load_dwordx2 v[42:43], v[38:39], off offset:64
	v_and_b32_e32 v27, 63, v30
	v_bfe_u32 v30, v30, 6, 7
	v_cndmask_b32_e32 v27, v27, v30, vcc
	v_lshl_or_b32 v27, v27, 8, v25
	global_load_dwordx4 v[30:33], v27, s[24:25]
	global_load_dwordx4 v[34:37], v27, s[24:25] offset:16
	s_add_i32 s3, s3, s56
	v_add_u32_e32 v26, s4, v26
	v_add_u32_e32 v24, s14, v24
	s_waitcnt vmcnt(6)
	v_lshlrev_b32_e32 v44, 16, v81
	v_and_b32_e32 v45, 0xffff0000, v81
	v_lshlrev_b32_e32 v48, 16, v80
	v_and_b32_e32 v49, 0xffff0000, v80
	v_lshlrev_b32_e32 v80, 16, v82
	v_and_b32_e32 v81, 0xffff0000, v82
	v_lshlrev_b32_e32 v46, 16, v83
	v_and_b32_e32 v47, 0xffff0000, v83
	v_pk_mul_f32 v[50:51], v[80:81], v[80:81]
	v_pk_mul_f32 v[82:83], v[46:47], v[46:47]
	v_pk_fma_f32 v[50:51], v[48:49], v[48:49], v[50:51]
	v_pk_fma_f32 v[82:83], v[44:45], v[44:45], v[82:83]
	v_add_f32_e32 v27, v50, v51
	v_add_f32_e32 v27, v82, v27
	v_add_f32_e32 v27, v83, v27
	v_mov_b32_e32 v52, v71
	v_mov_b32_e32 v71, v72
	v_add_f32_dpp v27, v27, v27 quad_perm:[1,0,3,2] row_mask:0xf bank_mask:0xf bound_ctrl:1
	v_mov_b32_e32 v53, v73
	v_mov_b32_e32 v73, v77
	v_add_f32_dpp v27, v27, v27 quad_perm:[2,3,0,1] row_mask:0xf bank_mask:0xf bound_ctrl:1
	s_nop 1
	v_add_f32_dpp v27, v27, v27 row_half_mirror row_mask:0xf bank_mask:0xf bound_ctrl:1
	s_nop 1
	v_add_f32_dpp v27, v27, v27 row_mirror row_mask:0xf bank_mask:0xf bound_ctrl:1
	v_fmamk_f32 v27, v27, 0x3c000000, v189
	v_mul_f32_e32 v72, 0x4b800000, v27
	v_cmp_gt_f32_e64 s[0:1], s2, v27
	s_nop 1
	v_cndmask_b32_e64 v27, v27, v72, s[0:1]
	v_rsq_f32_e32 v27, v27
	v_mov_b32_e32 v72, v75
	v_mov_b32_e32 v75, v76
	v_mul_f32_e32 v76, 0x45800000, v27
	v_cndmask_b32_e64 v76, v27, v76, s[0:1]
	v_pk_mul_f32 v[82:83], v[76:77], v[48:49] op_sel_hi:[0,1]
	v_pk_mul_f32 v[80:81], v[76:77], v[80:81] op_sel_hi:[0,1]
	v_pk_mul_f32 v[44:45], v[76:77], v[44:45] op_sel_hi:[0,1]
	v_pk_mul_f32 v[76:77], v[76:77], v[46:47] op_sel_hi:[0,1]
	v_pk_mul_f32 v[60:61], v[60:61], v[80:81]
	v_pk_mul_f32 v[62:63], v[62:63], v[76:77]
	v_pk_mul_f32 v[64:65], v[64:65], v[82:83]
	v_pk_mul_f32 v[66:67], v[66:67], v[44:45]
	v_pk_mul_f32 v[76:77], v[70:71], v[60:61]
	v_pk_mul_f32 v[60:61], v[52:53], v[60:61]
	v_pk_mul_f32 v[80:81], v[74:75], v[62:63]
	v_pk_mul_f32 v[62:63], v[72:73], v[62:63]
	v_pk_fma_f32 v[60:61], v[70:71], v[64:65], v[60:61] neg_lo:[0,0,1] neg_hi:[0,0,1]
	v_pk_fma_f32 v[62:63], v[74:75], v[66:67], v[62:63] neg_lo:[0,0,1] neg_hi:[0,0,1]
	v_pk_fma_f32 v[76:77], v[52:53], v[64:65], v[76:77]
	v_pk_fma_f32 v[64:65], v[72:73], v[66:67], v[80:81]
	v_cvt_pk_bf16_f32 v60, v60, v61
	v_cvt_pk_bf16_f32 v61, v62, v63
	v_cvt_pk_bf16_f32 v62, v76, v77
	v_cvt_pk_bf16_f32 v63, v64, v65
	global_store_dwordx2 v[78:79], v[60:61], off
	global_store_dwordx2 v[78:79], v[62:63], off offset:64
	s_cmp_lt_i32 s3, 0x14000
	s_cbranch_scc0 .Lpp_tailA
	v_mul_hi_i32 v60, v24, s17
	v_lshrrev_b32_e32 v61, 31, v60
	v_ashrrev_i32_e32 v60, 3, v60
	v_add_u32_e32 v70, v60, v61
	v_mad_u64_u32 v[60:61], s[0:1], v70, s18, v[24:25]
	v_cmp_lt_i32_e64 s[0:1], 15, v60
	v_ashrrev_i32_e32 v71, 31, v70
	v_mad_u64_u32 v[74:75], s[10:11], v70, s23, v[26:27]
	s_and_saveexec_b64 s[10:11], s[0:1]
	s_xor_b64 s[0:1], exec, s[10:11]
	v_lshlrev_b64 v[60:61], 10, v[70:71]
	v_lshl_add_u64 v[60:61], s[50:51], 0, v[60:61]
	v_add_u32_e32 v96, 0xfffff800, v74
	v_lshl_add_u64 v[72:73], v[96:97], 1, v[60:61]
	s_or_saveexec_b64 s[0:1], s[0:1]
	v_mov_b64_e32 v[62:63], v[14:15]
	v_mov_b64_e32 v[66:67], v[6:7]
	v_mov_b64_e32 v[60:61], v[12:13]
	v_mov_b64_e32 v[64:65], v[4:5]
	s_xor_b64 exec, exec, s[0:1]
	s_cbranch_execz .Lpp_join_4
	v_lshlrev_b64 v[60:61], 12, v[70:71]
	v_lshl_add_u64 v[60:61], s[48:49], 0, v[60:61]
	v_ashrrev_i32_e32 v75, 31, v74
	v_lshl_add_u64 v[72:73], v[74:75], 1, v[60:61]
	v_mov_b64_e32 v[62:63], v[10:11]
	v_mov_b64_e32 v[66:67], v[2:3]
	v_mov_b64_e32 v[60:61], v[8:9]
	v_mov_b64_e32 v[64:65], v[0:1]
.Lpp_join_4:
	s_or_b64 exec, exec, s[0:1]
	v_lshl_add_u64 v[78:79], v[72:73], 0, v[28:29]
	global_load_dwordx2 v[80:81], v[78:79], off
	global_load_dwordx2 v[82:83], v[78:79], off offset:64
	v_and_b32_e32 v27, 63, v70
	v_bfe_u32 v70, v70, 6, 7
	v_cndmask_b32_e32 v27, v27, v70, vcc
	v_lshl_or_b32 v27, v27, 8, v25
	global_load_dwordx4 v[70:73], v27, s[24:25]
	global_load_dwordx4 v[74:77], v27, s[24:25] offset:16
	s_add_i32 s3, s3, s56
	v_add_u32_e32 v26, s4, v26
	v_add_u32_e32 v24, s14, v24
	s_waitcnt vmcnt(6)
	v_lshlrev_b32_e32 v44, 16, v41
	v_and_b32_e32 v45, 0xffff0000, v41
	v_lshlrev_b32_e32 v48, 16, v40
	v_and_b32_e32 v49, 0xffff0000, v40
	v_lshlrev_b32_e32 v40, 16, v42
	v_and_b32_e32 v41, 0xffff0000, v42
	v_lshlrev_b32_e32 v46, 16, v43
	v_and_b32_e32 v47, 0xffff0000, v43
	v_pk_mul_f32 v[50:51], v[40:41], v[40:41]
	v_pk_mul_f32 v[42:43], v[46:47], v[46:47]
	v_pk_fma_f32 v[50:51], v[48:49], v[48:49], v[50:51]
	v_pk_fma_f32 v[42:43], v[44:45], v[44:45], v[42:43]
	v_add_f32_e32 v27, v50, v51
	v_add_f32_e32 v27, v42, v27
	v_add_f32_e32 v27, v43, v27
	v_mov_b32_e32 v52, v31
	v_mov_b32_e32 v31, v32
	v_add_f32_dpp v27, v27, v27 quad_perm:[1,0,3,2] row_mask:0xf bank_mask:0xf bound_ctrl:1
	v_mov_b32_e32 v53, v33
	v_mov_b32_e32 v33, v37
	v_add_f32_dpp v27, v27, v27 quad_perm:[2,3,0,1] row_mask:0xf bank_mask:0xf bound_ctrl:1
	s_nop 1
	v_add_f32_dpp v27, v27, v27 row_half_mirror row_mask:0xf bank_mask:0xf bound_ctrl:1
	s_nop 1
	v_add_f32_dpp v27, v27, v27 row_mirror row_mask:0xf bank_mask:0xf bound_ctrl:1
	v_fmamk_f32 v27, v27, 0x3c000000, v189
	v_mul_f32_e32 v32, 0x4b800000, v27
	v_cmp_gt_f32_e64 s[0:1], s2, v27
	s_nop 1
	v_cndmask_b32_e64 v27, v27, v32, s[0:1]
	v_rsq_f32_e32 v27, v27
	v_mov_b32_e32 v32, v35
	v_mov_b32_e32 v35, v36
	v_mul_f32_e32 v36, 0x45800000, v27
	v_cndmask_b32_e64 v36, v27, v36, s[0:1]
	v_pk_mul_f32 v[42:43], v[36:37], v[48:49] op_sel_hi:[0,1]
	v_pk_mul_f32 v[40:41], v[36:37], v[40:41] op_sel_hi:[0,1]
	v_pk_mul_f32 v[44:45], v[36:37], v[44:45] op_sel_hi:[0,1]
	v_pk_mul_f32 v[36:37], v[36:37], v[46:47] op_sel_hi:[0,1]
	v_pk_mul_f32 v[16:17], v[16:17], v[40:41]
	v_pk_mul_f32 v[18:19], v[18:19], v[36:37]
	v_pk_mul_f32 v[20:21], v[20:21], v[42:43]
	v_pk_mul_f32 v[22:23], v[22:23], v[44:45]
	v_pk_mul_f32 v[36:37], v[30:31], v[16:17]
	v_pk_mul_f32 v[16:17], v[52:53], v[16:17]
	v_pk_mul_f32 v[40:41], v[34:35], v[18:19]
	v_pk_mul_f32 v[18:19], v[32:33], v[18:19]
	v_pk_fma_f32 v[16:17], v[30:31], v[20:21], v[16:17] neg_lo:[0,0,1] neg_hi:[0,0,1]
	v_pk_fma_f32 v[18:19], v[34:35], v[22:23], v[18:19] neg_lo:[0,0,1] neg_hi:[0,0,1]
	v_pk_fma_f32 v[36:37], v[52:53], v[20:21], v[36:37]
	v_pk_fma_f32 v[20:21], v[32:33], v[22:23], v[40:41]
	v_cvt_pk_bf16_f32 v16, v16, v17
	v_cvt_pk_bf16_f32 v17, v18, v19
	v_cvt_pk_bf16_f32 v18, v36, v37
	v_cvt_pk_bf16_f32 v19, v20, v21
	global_store_dwordx2 v[38:39], v[16:17], off
	global_store_dwordx2 v[38:39], v[18:19], off offset:64
	s_branch .Lpp_loop
.Lpp_tailA:
	s_waitcnt vmcnt(0)
	v_lshlrev_b32_e32 v44, 16, v41
	v_and_b32_e32 v45, 0xffff0000, v41
	v_lshlrev_b32_e32 v48, 16, v40
	v_and_b32_e32 v49, 0xffff0000, v40
	v_lshlrev_b32_e32 v40, 16, v42
	v_and_b32_e32 v41, 0xffff0000, v42
	v_lshlrev_b32_e32 v46, 16, v43
	v_and_b32_e32 v47, 0xffff0000, v43
	v_pk_mul_f32 v[50:51], v[40:41], v[40:41]
	v_pk_mul_f32 v[42:43], v[46:47], v[46:47]
	v_pk_fma_f32 v[50:51], v[48:49], v[48:49], v[50:51]
	v_pk_fma_f32 v[42:43], v[44:45], v[44:45], v[42:43]
	v_add_f32_e32 v27, v50, v51
	v_add_f32_e32 v27, v42, v27
	v_add_f32_e32 v27, v43, v27
	v_mov_b32_e32 v52, v31
	v_mov_b32_e32 v31, v32
	v_add_f32_dpp v27, v27, v27 quad_perm:[1,0,3,2] row_mask:0xf bank_mask:0xf bound_ctrl:1
	v_mov_b32_e32 v53, v33
	v_mov_b32_e32 v33, v37
	v_add_f32_dpp v27, v27, v27 quad_perm:[2,3,0,1] row_mask:0xf bank_mask:0xf bound_ctrl:1
	s_nop 1
	v_add_f32_dpp v27, v27, v27 row_half_mirror row_mask:0xf bank_mask:0xf bound_ctrl:1
	s_nop 1
	v_add_f32_dpp v27, v27, v27 row_mirror row_mask:0xf bank_mask:0xf bound_ctrl:1
	v_fmamk_f32 v27, v27, 0x3c000000, v189
	v_mul_f32_e32 v32, 0x4b800000, v27
	v_cmp_gt_f32_e64 s[0:1], s2, v27
	s_nop 1
	v_cndmask_b32_e64 v27, v27, v32, s[0:1]
	v_rsq_f32_e32 v27, v27
	v_mov_b32_e32 v32, v35
	v_mov_b32_e32 v35, v36
	v_mul_f32_e32 v36, 0x45800000, v27
	v_cndmask_b32_e64 v36, v27, v36, s[0:1]
	v_pk_mul_f32 v[42:43], v[36:37], v[48:49] op_sel_hi:[0,1]
	v_pk_mul_f32 v[40:41], v[36:37], v[40:41] op_sel_hi:[0,1]
	v_pk_mul_f32 v[44:45], v[36:37], v[44:45] op_sel_hi:[0,1]
	v_pk_mul_f32 v[36:37], v[36:37], v[46:47] op_sel_hi:[0,1]
	v_pk_mul_f32 v[16:17], v[16:17], v[40:41]
	v_pk_mul_f32 v[18:19], v[18:19], v[36:37]
	v_pk_mul_f32 v[20:21], v[20:21], v[42:43]
	v_pk_mul_f32 v[22:23], v[22:23], v[44:45]
	v_pk_mul_f32 v[36:37], v[30:31], v[16:17]
	v_pk_mul_f32 v[16:17], v[52:53], v[16:17]
	v_pk_mul_f32 v[40:41], v[34:35], v[18:19]
	v_pk_mul_f32 v[18:19], v[32:33], v[18:19]
	v_pk_fma_f32 v[16:17], v[30:31], v[20:21], v[16:17] neg_lo:[0,0,1] neg_hi:[0,0,1]
	v_pk_fma_f32 v[18:19], v[34:35], v[22:23], v[18:19] neg_lo:[0,0,1] neg_hi:[0,0,1]
	v_pk_fma_f32 v[36:37], v[52:53], v[20:21], v[36:37]
	v_pk_fma_f32 v[20:21], v[32:33], v[22:23], v[40:41]
	v_cvt_pk_bf16_f32 v16, v16, v17
	v_cvt_pk_bf16_f32 v17, v18, v19
	v_cvt_pk_bf16_f32 v18, v36, v37
	v_cvt_pk_bf16_f32 v19, v20, v21
	global_store_dwordx2 v[38:39], v[16:17], off
	global_store_dwordx2 v[38:39], v[18:19], off offset:64
	s_branch .LBB0_84
.Lpp_tailB:
	s_waitcnt vmcnt(0)
	v_lshlrev_b32_e32 v44, 16, v81
	v_and_b32_e32 v45, 0xffff0000, v81
	v_lshlrev_b32_e32 v48, 16, v80
	v_and_b32_e32 v49, 0xffff0000, v80
	v_lshlrev_b32_e32 v80, 16, v82
	v_and_b32_e32 v81, 0xffff0000, v82
	v_lshlrev_b32_e32 v46, 16, v83
	v_and_b32_e32 v47, 0xffff0000, v83
	v_pk_mul_f32 v[50:51], v[80:81], v[80:81]
	v_pk_mul_f32 v[82:83], v[46:47], v[46:47]
	v_pk_fma_f32 v[50:51], v[48:49], v[48:49], v[50:51]
	v_pk_fma_f32 v[82:83], v[44:45], v[44:45], v[82:83]
	v_add_f32_e32 v27, v50, v51
	v_add_f32_e32 v27, v82, v27
	v_add_f32_e32 v27, v83, v27
	v_mov_b32_e32 v52, v71
	v_mov_b32_e32 v71, v72
	v_add_f32_dpp v27, v27, v27 quad_perm:[1,0,3,2] row_mask:0xf bank_mask:0xf bound_ctrl:1
	v_mov_b32_e32 v53, v73
	v_mov_b32_e32 v73, v77
	v_add_f32_dpp v27, v27, v27 quad_perm:[2,3,0,1] row_mask:0xf bank_mask:0xf bound_ctrl:1
	s_nop 1
	v_add_f32_dpp v27, v27, v27 row_half_mirror row_mask:0xf bank_mask:0xf bound_ctrl:1
	s_nop 1
	v_add_f32_dpp v27, v27, v27 row_mirror row_mask:0xf bank_mask:0xf bound_ctrl:1
	v_fmamk_f32 v27, v27, 0x3c000000, v189
	v_mul_f32_e32 v72, 0x4b800000, v27
	v_cmp_gt_f32_e64 s[0:1], s2, v27
	s_nop 1
	v_cndmask_b32_e64 v27, v27, v72, s[0:1]
	v_rsq_f32_e32 v27, v27
	v_mov_b32_e32 v72, v75
	v_mov_b32_e32 v75, v76
	v_mul_f32_e32 v76, 0x45800000, v27
	v_cndmask_b32_e64 v76, v27, v76, s[0:1]
	v_pk_mul_f32 v[82:83], v[76:77], v[48:49] op_sel_hi:[0,1]
	v_pk_mul_f32 v[80:81], v[76:77], v[80:81] op_sel_hi:[0,1]
	v_pk_mul_f32 v[44:45], v[76:77], v[44:45] op_sel_hi:[0,1]
	v_pk_mul_f32 v[76:77], v[76:77], v[46:47] op_sel_hi:[0,1]
	v_pk_mul_f32 v[60:61], v[60:61], v[80:81]
	v_pk_mul_f32 v[62:63], v[62:63], v[76:77]
	v_pk_mul_f32 v[64:65], v[64:65], v[82:83]
	v_pk_mul_f32 v[66:67], v[66:67], v[44:45]
	v_pk_mul_f32 v[76:77], v[70:71], v[60:61]
	v_pk_mul_f32 v[60:61], v[52:53], v[60:61]
	v_pk_mul_f32 v[80:81], v[74:75], v[62:63]
	v_pk_mul_f32 v[62:63], v[72:73], v[62:63]
	v_pk_fma_f32 v[60:61], v[70:71], v[64:65], v[60:61] neg_lo:[0,0,1] neg_hi:[0,0,1]
	v_pk_fma_f32 v[62:63], v[74:75], v[66:67], v[62:63] neg_lo:[0,0,1] neg_hi:[0,0,1]
	v_pk_fma_f32 v[76:77], v[52:53], v[64:65], v[76:77]
	v_pk_fma_f32 v[64:65], v[72:73], v[66:67], v[80:81]
	v_cvt_pk_bf16_f32 v60, v60, v61
	v_cvt_pk_bf16_f32 v61, v62, v63
	v_cvt_pk_bf16_f32 v62, v76, v77
	v_cvt_pk_bf16_f32 v63, v64, v65
	global_store_dwordx2 v[78:79], v[60:61], off
	global_store_dwordx2 v[78:79], v[62:63], off offset:64

.LBB0_146:
	v_mov_b32_e32 v36, v188
	s_nop 0
	v_readfirstlane_b32 s0, v36
	s_ashr_i32 s12, s0, 6
	s_lshl_b32 s0, s3, 6
	s_and_b32 s11, s0, 0x780
	s_and_b32 s10, s0, 64
	s_cmp_lt_u32 s3, 64
	s_cselect_b64 s[36:37], -1, 0
	s_lshl_b32 s0, s3, 8
	s_and_b32 s4, s0, 0x2000
	v_and_b32_e32 v110, 15, v36
	v_lshrrev_b32_e32 v104, 4, v36
	v_bfe_u32 v106, v36, 4, 2
	s_cmp_lt_i32 s12, 4
	s_mov_b64 s[0:1], -1
	s_cbranch_scc0 .LBB0_153
	s_and_b64 s[14:15], s[36:37], exec
	s_cselect_b32 s1, 0, 0x4000000
	s_add_u32 s1, s88, s1
	s_addc_u32 s13, s89, 0
	s_lshl_b32 s14, s11, 1
	s_add_u32 s1, s1, s14
	s_addc_u32 s13, s13, 0
	s_lshl_b32 s14, s10, 1
	s_add_u32 s1, s1, s14
	s_addc_u32 s13, s13, 0
	s_lshl_b32 s14, s12, 4
	s_ashr_i32 s15, s14, 31
	s_lshl_b64 s[14:15], s[14:15], 1
	s_waitcnt lgkmcnt(0)
	v_lshlrev_b32_e32 v2, 3, v106
	s_add_u32 s14, s1, s14
	s_movk_i32 s1, 0x90
	v_mad_u32_u24 v3, v110, s1, v2
	v_readlane_b32 s1, v247, 63
	s_mulk_i32 s12, 0x900
	s_addc_u32 s15, s13, s15
	v_add_u32_e32 v40, s1, v3
	s_add_i32 s1, s12, 0
	v_cmp_gt_u32_e32 vcc, 2, v106
	s_add_i32 s1, s1, 0xd000
	v_add_u32_e32 v41, s1, v3
	v_cndmask_b32_e64 v0, v195, 0, vcc
	s_movk_i32 s1, 0x110
	v_lshlrev_b32_e32 v1, 3, v104
	v_lshlrev_b32_e32 v96, 1, v110
	v_mad_u32_u24 v0, v110, s1, v0
	v_lshl_add_u64 v[32:33], s[14:15], 0, v[96:97]
	v_mul_u32_u24_e32 v3, 0x110, v110
	v_and_or_b32 v0, v1, 8, v0
	v_readlane_b32 s1, v248, 0
	v_mov_b32_e32 v96, v97
	v_lshlrev_b32_e32 v37, 2, v106
	v_add_u32_e32 v42, s1, v0
	v_add3_u32 v43, v3, v2, 0
	v_mov_b32_e32 v98, v97
	s_waitcnt vmcnt(0)
	v_mov_b32_e32 v99, v97
	v_mov_b64_e32 v[0:1], v[96:97]
	v_mov_b64_e32 v[4:5], v[96:97]
	v_mov_b64_e32 v[8:9], v[96:97]
	v_mov_b64_e32 v[12:13], v[96:97]
	v_mov_b64_e32 v[16:17], v[96:97]
	v_mov_b64_e32 v[20:21], v[96:97]
	v_mov_b64_e32 v[24:25], v[96:97]
	v_mov_b64_e32 v[28:29], v[96:97]
	v_mov_b64_e32 v[2:3], v[98:99]
	v_mov_b64_e32 v[6:7], v[98:99]
	v_mov_b64_e32 v[10:11], v[98:99]
	v_mov_b64_e32 v[14:15], v[98:99]
	v_mov_b64_e32 v[18:19], v[98:99]
	v_mov_b64_e32 v[22:23], v[98:99]
	v_mov_b64_e32 v[26:27], v[98:99]
	v_mov_b64_e32 v[30:31], v[98:99]
	v_lshl_add_u32 v38, v106, 4, s73
	v_xor_b32_e32 v39, 0x203c, v37
	s_lshl_b32 s1, s4, 12
	s_add_u32 s14, s14, s1
	s_addc_u32 s15, s15, 0
	s_mov_b32 s13, 0x10000
	s_cmp_lt_u32 s3, 64
	s_cselect_b32 s13, s13, 0xffff0000
	s_ashr_i32 s1, s13, 4
	v_add_u32_e32 v58, 0xffffffc3, v39
	v_cndmask_b32_e64 v58, v58, v37, s[36:37]
	v_lshlrev_b32_e32 v58, 12, v58
	v_lshl_add_u32 v160, v110, 1, v58
	v_add_u32_e32 v161, s1, v160
	v_add_u32_e32 v162, s1, v161
	v_add_u32_e32 v163, s1, v162
	s_lshl_b32 s1, s11, 1
	s_add_u32 s16, s76, s1
	s_addc_u32 s17, s77, 0
	s_lshl_b32 s18, s13, 2
	v_and_b32_e32 v169, 63, v36
	v_lshrrev_b32_e32 v170, 6, v36
	v_lshlrev_b32_e32 v170, 4, v170
	v_bfe_u32 v171, v169, 1, 4
	v_add_u32_e32 v171, v170, v171
	v_and_b32_e32 v172, 15, v169
	v_add_u32_e32 v172, v170, v172
	v_sub_u32_e32 v170, 0x1fff, v171
	v_cndmask_b32_e64 v171, v170, v171, s[36:37]
	v_sub_u32_e32 v170, 0x1fff, v172
	v_cndmask_b32_e64 v172, v170, v172, s[36:37]
	v_add_u32_e32 v171, s4, v171
	v_add_u32_e32 v172, s4, v172
	v_lshlrev_b32_e32 v171, 12, v171
	v_lshlrev_b32_e32 v172, 12, v172
	v_and_b32_e32 v170, 1, v169
	v_lshl_or_b32 v171, v170, 7, v171
	s_mov_b32 s1, 0x8000000
	s_cmp_lt_u32 s3, 64
	s_cselect_b32 s1, s1, 0xc000000
	v_mov_b32_e32 v170, s1
	v_cmp_gt_u32_e32 vcc, 32, v169
	s_nop 1
	v_cndmask_b32_e32 v170, 0, v170, vcc
	v_add_u32_e32 v171, v170, v171
	s_lshl_b32 s1, s10, 1
	s_add_u32 s1, s1, 0x4000000
	v_add_u32_e32 v172, s1, v172
	s_mul_i32 s1, s18, 5
	v_add_u32_e32 v171, s1, v171
	v_add_u32_e32 v172, s1, v172
	s_mov_b32 s0, 1
	s_barrier
.Lhc_stage:
	s_bitcmp1_b32 s0, 0
	s_cselect_b32 s12, 0, 0xfc00
	s_cmpk_gt_u32 s0, 0x7b
	s_cbranch_scc1 .Lhc_nopf
	global_load_dword v167, v171, s[16:17]
	global_load_dword v168, v172, s[16:17]
	v_add_u32_e32 v171, s18, v171
	v_add_u32_e32 v172, s18, v172
.Lhc_nopf:
	v_add_u32_e32 v45, s12, v42
	v_add_u32_e32 v46, s12, v41
	v_add_u32_e32 v44, s12, v43
	v_add_u32_e32 v49, s12, v38
	v_add_u32_e32 v47, s12, v40
	ds_read_b64 v[62:63], v45 offset:0
	ds_read_b64 v[34:35], v46 offset:0
	ds_read2_b64 v[68:71], v44 offset0:0 offset1:4
	ds_read2_b64 v[72:75], v44 offset0:8 offset1:12
	ds_read2_b64 v[76:79], v44 offset0:16 offset1:20
	ds_read2_b64 v[80:83], v44 offset0:24 offset1:28
	v_add_u32_e32 v164, 0x1100, v44
	v_add_u32_e32 v165, 0x2200, v44
	v_add_u32_e32 v166, 0x3300, v44
	ds_read_b128 v[112:115], v49 offset:0
	ds_read_b64 v[144:145], v47 offset:0
	ds_read_b128 v[116:119], v49 offset:64
	ds_read_b64 v[146:147], v47 offset:2304
	ds_read_b128 v[120:123], v49 offset:128
	ds_read_b64 v[148:149], v47 offset:4608
	ds_read_b128 v[124:127], v49 offset:192
	ds_read_b64 v[150:151], v47 offset:6912
	v_cvt_pk_bf16_f32 v84, v28, v29
	v_cvt_pk_bf16_f32 v85, v30, v31
	v_cvt_pk_bf16_f32 v86, v24, v25
	v_cvt_pk_bf16_f32 v87, v26, v27
	s_waitcnt lgkmcnt(8)
	v_mfma_f32_16x16x16_bf16 v[50:53], v[62:63], v[34:35], 0
	v_cvt_pk_bf16_f32 v88, v20, v21
	v_cvt_pk_bf16_f32 v89, v22, v23
	v_mfma_f32_16x16x16_bf16 v[50:53], v[68:69], v[84:85], v[50:53]
	v_mfma_f32_16x16x16_bf16 v[54:57], v[70:71], v[86:87], 0
	v_cvt_pk_bf16_f32 v90, v16, v17
	v_cvt_pk_bf16_f32 v91, v18, v19
	ds_read_b128 v[128:131], v49 offset:256
	ds_read_b64 v[152:153], v47 offset:9216
	v_mfma_f32_16x16x16_bf16 v[50:53], v[72:73], v[88:89], v[50:53]
	v_cvt_pk_bf16_f32 v92, v12, v13
	v_cvt_pk_bf16_f32 v93, v14, v15
	ds_read_b128 v[132:135], v49 offset:320
	ds_read_b64 v[154:155], v47 offset:11520
	v_mfma_f32_16x16x16_bf16 v[54:57], v[74:75], v[90:91], v[54:57]
	v_cvt_pk_bf16_f32 v94, v8, v9
	v_cvt_pk_bf16_f32 v95, v10, v11
	ds_read_b128 v[136:139], v49 offset:384
	ds_read_b64 v[156:157], v47 offset:13824
	v_mfma_f32_16x16x16_bf16 v[50:53], v[76:77], v[92:93], v[50:53]
	v_cvt_pk_bf16_f32 v100, v4, v5
	v_cvt_pk_bf16_f32 v101, v6, v7
	ds_read_b128 v[140:143], v49 offset:448
	ds_read_b64 v[158:159], v47 offset:16128
	v_mfma_f32_16x16x16_bf16 v[54:57], v[78:79], v[94:95], v[54:57]
	v_cvt_pk_bf16_f32 v102, v0, v1
	v_cvt_pk_bf16_f32 v103, v2, v3
	v_mfma_f32_16x16x16_bf16 v[50:53], v[80:81], v[100:101], v[50:53]
	ds_read_b64 v[62:63], v45 offset:4352
	v_mfma_f32_16x16x16_bf16 v[54:57], v[82:83], v[102:103], v[54:57]
	ds_read_b64 v[60:61], v46 offset:32
	ds_read2_b64 v[68:71], v164 offset0:0 offset1:4
	ds_read2_b64 v[72:75], v164 offset0:8 offset1:12
	ds_read2_b64 v[76:79], v164 offset0:16 offset1:20
	ds_read2_b64 v[80:83], v164 offset0:24 offset1:28
	s_nop 2
	v_pk_add_f32 v[52:53], v[52:53], v[56:57]
	v_pk_add_f32 v[50:51], v[50:51], v[54:55]
	v_cvt_pk_bf16_f32 v59, v52, v53
	v_cvt_pk_bf16_f32 v58, v50, v51
	global_store_short v160, v58, s[14:15]
	global_store_short_d16_hi v161, v58, s[14:15]
	global_store_short v162, v59, s[14:15]
	global_store_short_d16_hi v163, v59, s[14:15]
	v_add_u32_e32 v160, s13, v160
	v_add_u32_e32 v161, s13, v161
	v_add_u32_e32 v162, s13, v162
	v_add_u32_e32 v163, s13, v163
	s_waitcnt lgkmcnt(6)
	v_pk_mul_f32 v[30:31], v[30:31], v[114:115]
	v_pk_mul_f32 v[28:29], v[28:29], v[112:113]
	v_pk_mul_f32 v[26:27], v[26:27], v[118:119]
	v_pk_mul_f32 v[24:25], v[24:25], v[116:117]
	v_mfma_f32_16x16x16_bf16 v[28:31], v[144:145], v[34:35], v[28:31]
	v_pk_mul_f32 v[22:23], v[22:23], v[122:123]
	v_pk_mul_f32 v[20:21], v[20:21], v[120:121]
	v_mfma_f32_16x16x16_bf16 v[24:27], v[146:147], v[34:35], v[24:27]
	v_pk_mul_f32 v[18:19], v[18:19], v[126:127]
	v_pk_mul_f32 v[16:17], v[16:17], v[124:125]
	v_mfma_f32_16x16x16_bf16 v[20:23], v[148:149], v[34:35], v[20:23]
	v_pk_mul_f32 v[14:15], v[14:15], v[130:131]
	v_pk_mul_f32 v[12:13], v[12:13], v[128:129]
	v_mfma_f32_16x16x16_bf16 v[16:19], v[150:151], v[34:35], v[16:19]
	v_pk_mul_f32 v[10:11], v[10:11], v[134:135]
	v_pk_mul_f32 v[8:9], v[8:9], v[132:133]
	v_mfma_f32_16x16x16_bf16 v[12:15], v[152:153], v[34:35], v[12:15]
	v_pk_mul_f32 v[6:7], v[6:7], v[138:139]
	v_pk_mul_f32 v[4:5], v[4:5], v[136:137]
	v_mfma_f32_16x16x16_bf16 v[8:11], v[154:155], v[34:35], v[8:11]
	v_pk_mul_f32 v[2:3], v[2:3], v[142:143]
	v_pk_mul_f32 v[0:1], v[0:1], v[140:141]
	v_mfma_f32_16x16x16_bf16 v[4:7], v[156:157], v[34:35], v[4:7]
	s_nop 1
	v_mfma_f32_16x16x16_bf16 v[0:3], v[158:159], v[34:35], v[0:3]
	ds_read_b128 v[112:115], v49 offset:512
	ds_read_b64 v[144:145], v47 offset:32
	ds_read_b128 v[116:119], v49 offset:576
	ds_read_b64 v[146:147], v47 offset:2336
	ds_read_b128 v[120:123], v49 offset:640
	ds_read_b64 v[148:149], v47 offset:4640
	ds_read_b128 v[124:127], v49 offset:704
	ds_read_b64 v[150:151], v47 offset:6944
	v_cvt_pk_bf16_f32 v84, v28, v29
	v_cvt_pk_bf16_f32 v85, v30, v31
	v_cvt_pk_bf16_f32 v86, v24, v25
	v_cvt_pk_bf16_f32 v87, v26, v27
	s_waitcnt lgkmcnt(8)
	v_mfma_f32_16x16x16_bf16 v[50:53], v[62:63], v[60:61], 0
	v_cvt_pk_bf16_f32 v88, v20, v21
	v_cvt_pk_bf16_f32 v89, v22, v23
	v_mfma_f32_16x16x16_bf16 v[50:53], v[68:69], v[84:85], v[50:53]
	v_mfma_f32_16x16x16_bf16 v[54:57], v[70:71], v[86:87], 0
	v_cvt_pk_bf16_f32 v90, v16, v17
	v_cvt_pk_bf16_f32 v91, v18, v19
	ds_read_b128 v[128:131], v49 offset:768
	ds_read_b64 v[152:153], v47 offset:9248
	v_mfma_f32_16x16x16_bf16 v[50:53], v[72:73], v[88:89], v[50:53]
	v_cvt_pk_bf16_f32 v92, v12, v13
	v_cvt_pk_bf16_f32 v93, v14, v15
	ds_read_b128 v[132:135], v49 offset:832
	ds_read_b64 v[154:155], v47 offset:11552
	v_mfma_f32_16x16x16_bf16 v[54:57], v[74:75], v[90:91], v[54:57]
	v_cvt_pk_bf16_f32 v94, v8, v9
	v_cvt_pk_bf16_f32 v95, v10, v11
	ds_read_b128 v[136:139], v49 offset:896
	ds_read_b64 v[156:157], v47 offset:13856
	v_mfma_f32_16x16x16_bf16 v[50:53], v[76:77], v[92:93], v[50:53]
	v_cvt_pk_bf16_f32 v100, v4, v5
	v_cvt_pk_bf16_f32 v101, v6, v7
	ds_read_b128 v[140:143], v49 offset:960
	ds_read_b64 v[158:159], v47 offset:16160
	v_mfma_f32_16x16x16_bf16 v[54:57], v[78:79], v[94:95], v[54:57]
	v_cvt_pk_bf16_f32 v102, v0, v1
	v_cvt_pk_bf16_f32 v103, v2, v3
	v_mfma_f32_16x16x16_bf16 v[50:53], v[80:81], v[100:101], v[50:53]
	ds_read_b64 v[62:63], v45 offset:8704
	v_mfma_f32_16x16x16_bf16 v[54:57], v[82:83], v[102:103], v[54:57]
	ds_read_b64 v[34:35], v46 offset:64
	ds_read2_b64 v[68:71], v165 offset0:0 offset1:4
	ds_read2_b64 v[72:75], v165 offset0:8 offset1:12
	ds_read2_b64 v[76:79], v165 offset0:16 offset1:20
	ds_read2_b64 v[80:83], v165 offset0:24 offset1:28
	s_nop 2
	v_pk_add_f32 v[52:53], v[52:53], v[56:57]
	v_pk_add_f32 v[50:51], v[50:51], v[54:55]
	v_cvt_pk_bf16_f32 v59, v52, v53
	v_cvt_pk_bf16_f32 v58, v50, v51
	global_store_short v160, v58, s[14:15]
	global_store_short_d16_hi v161, v58, s[14:15]
	global_store_short v162, v59, s[14:15]
	global_store_short_d16_hi v163, v59, s[14:15]
	v_add_u32_e32 v160, s13, v160
	v_add_u32_e32 v161, s13, v161
	v_add_u32_e32 v162, s13, v162
	v_add_u32_e32 v163, s13, v163
	s_waitcnt lgkmcnt(6)
	v_pk_mul_f32 v[30:31], v[30:31], v[114:115]
	v_pk_mul_f32 v[28:29], v[28:29], v[112:113]
	v_pk_mul_f32 v[26:27], v[26:27], v[118:119]
	v_pk_mul_f32 v[24:25], v[24:25], v[116:117]
	v_mfma_f32_16x16x16_bf16 v[28:31], v[144:145], v[60:61], v[28:31]
	v_pk_mul_f32 v[22:23], v[22:23], v[122:123]
	v_pk_mul_f32 v[20:21], v[20:21], v[120:121]
	v_mfma_f32_16x16x16_bf16 v[24:27], v[146:147], v[60:61], v[24:27]
	v_pk_mul_f32 v[18:19], v[18:19], v[126:127]
	v_pk_mul_f32 v[16:17], v[16:17], v[124:125]
	v_mfma_f32_16x16x16_bf16 v[20:23], v[148:149], v[60:61], v[20:23]
	v_pk_mul_f32 v[14:15], v[14:15], v[130:131]
	v_pk_mul_f32 v[12:13], v[12:13], v[128:129]
	v_mfma_f32_16x16x16_bf16 v[16:19], v[150:151], v[60:61], v[16:19]
	v_pk_mul_f32 v[10:11], v[10:11], v[134:135]
	v_pk_mul_f32 v[8:9], v[8:9], v[132:133]
	v_mfma_f32_16x16x16_bf16 v[12:15], v[152:153], v[60:61], v[12:15]
	v_pk_mul_f32 v[6:7], v[6:7], v[138:139]
	v_pk_mul_f32 v[4:5], v[4:5], v[136:137]
	v_mfma_f32_16x16x16_bf16 v[8:11], v[154:155], v[60:61], v[8:11]
	v_pk_mul_f32 v[2:3], v[2:3], v[142:143]
	v_pk_mul_f32 v[0:1], v[0:1], v[140:141]
	v_mfma_f32_16x16x16_bf16 v[4:7], v[156:157], v[60:61], v[4:7]
	s_nop 1
	v_mfma_f32_16x16x16_bf16 v[0:3], v[158:159], v[60:61], v[0:3]
	ds_read_b128 v[112:115], v49 offset:1024
	ds_read_b64 v[144:145], v47 offset:64
	ds_read_b128 v[116:119], v49 offset:1088
	ds_read_b64 v[146:147], v47 offset:2368
	ds_read_b128 v[120:123], v49 offset:1152
	ds_read_b64 v[148:149], v47 offset:4672
	ds_read_b128 v[124:127], v49 offset:1216
	ds_read_b64 v[150:151], v47 offset:6976
	v_cvt_pk_bf16_f32 v84, v28, v29
	v_cvt_pk_bf16_f32 v85, v30, v31
	v_cvt_pk_bf16_f32 v86, v24, v25
	v_cvt_pk_bf16_f32 v87, v26, v27
	s_waitcnt lgkmcnt(8)
	v_mfma_f32_16x16x16_bf16 v[50:53], v[62:63], v[34:35], 0
	v_cvt_pk_bf16_f32 v88, v20, v21
	v_cvt_pk_bf16_f32 v89, v22, v23
	v_mfma_f32_16x16x16_bf16 v[50:53], v[68:69], v[84:85], v[50:53]
	v_mfma_f32_16x16x16_bf16 v[54:57], v[70:71], v[86:87], 0
	v_cvt_pk_bf16_f32 v90, v16, v17
	v_cvt_pk_bf16_f32 v91, v18, v19
	ds_read_b128 v[128:131], v49 offset:1280
	ds_read_b64 v[152:153], v47 offset:9280
	v_mfma_f32_16x16x16_bf16 v[50:53], v[72:73], v[88:89], v[50:53]
	v_cvt_pk_bf16_f32 v92, v12, v13
	v_cvt_pk_bf16_f32 v93, v14, v15
	ds_read_b128 v[132:135], v49 offset:1344
	ds_read_b64 v[154:155], v47 offset:11584
	v_mfma_f32_16x16x16_bf16 v[54:57], v[74:75], v[90:91], v[54:57]
	v_cvt_pk_bf16_f32 v94, v8, v9
	v_cvt_pk_bf16_f32 v95, v10, v11
	ds_read_b128 v[136:139], v49 offset:1408
	ds_read_b64 v[156:157], v47 offset:13888
	v_mfma_f32_16x16x16_bf16 v[50:53], v[76:77], v[92:93], v[50:53]
	v_cvt_pk_bf16_f32 v100, v4, v5
	v_cvt_pk_bf16_f32 v101, v6, v7
	ds_read_b128 v[140:143], v49 offset:1472
	ds_read_b64 v[158:159], v47 offset:16192
	v_mfma_f32_16x16x16_bf16 v[54:57], v[78:79], v[94:95], v[54:57]
	v_cvt_pk_bf16_f32 v102, v0, v1
	v_cvt_pk_bf16_f32 v103, v2, v3
	v_mfma_f32_16x16x16_bf16 v[50:53], v[80:81], v[100:101], v[50:53]
	ds_read_b64 v[62:63], v45 offset:13056
	v_mfma_f32_16x16x16_bf16 v[54:57], v[82:83], v[102:103], v[54:57]
	ds_read_b64 v[60:61], v46 offset:96
	ds_read2_b64 v[68:71], v166 offset0:0 offset1:4
	ds_read2_b64 v[72:75], v166 offset0:8 offset1:12
	ds_read2_b64 v[76:79], v166 offset0:16 offset1:20
	ds_read2_b64 v[80:83], v166 offset0:24 offset1:28
	s_nop 2
	v_pk_add_f32 v[52:53], v[52:53], v[56:57]
	v_pk_add_f32 v[50:51], v[50:51], v[54:55]
	v_cvt_pk_bf16_f32 v59, v52, v53
	v_cvt_pk_bf16_f32 v58, v50, v51
	global_store_short v160, v58, s[14:15]
	global_store_short_d16_hi v161, v58, s[14:15]
	global_store_short v162, v59, s[14:15]
	global_store_short_d16_hi v163, v59, s[14:15]
	v_add_u32_e32 v160, s13, v160
	v_add_u32_e32 v161, s13, v161
	v_add_u32_e32 v162, s13, v162
	v_add_u32_e32 v163, s13, v163
	s_waitcnt lgkmcnt(6)
	v_pk_mul_f32 v[30:31], v[30:31], v[114:115]
	v_pk_mul_f32 v[28:29], v[28:29], v[112:113]
	v_pk_mul_f32 v[26:27], v[26:27], v[118:119]
	v_pk_mul_f32 v[24:25], v[24:25], v[116:117]
	v_mfma_f32_16x16x16_bf16 v[28:31], v[144:145], v[34:35], v[28:31]
	v_pk_mul_f32 v[22:23], v[22:23], v[122:123]
	v_pk_mul_f32 v[20:21], v[20:21], v[120:121]
	v_mfma_f32_16x16x16_bf16 v[24:27], v[146:147], v[34:35], v[24:27]
	v_pk_mul_f32 v[18:19], v[18:19], v[126:127]
	v_pk_mul_f32 v[16:17], v[16:17], v[124:125]
	v_mfma_f32_16x16x16_bf16 v[20:23], v[148:149], v[34:35], v[20:23]
	v_pk_mul_f32 v[14:15], v[14:15], v[130:131]
	v_pk_mul_f32 v[12:13], v[12:13], v[128:129]
	v_mfma_f32_16x16x16_bf16 v[16:19], v[150:151], v[34:35], v[16:19]
	v_pk_mul_f32 v[10:11], v[10:11], v[134:135]
	v_pk_mul_f32 v[8:9], v[8:9], v[132:133]
	v_mfma_f32_16x16x16_bf16 v[12:15], v[152:153], v[34:35], v[12:15]
	v_pk_mul_f32 v[6:7], v[6:7], v[138:139]
	v_pk_mul_f32 v[4:5], v[4:5], v[136:137]
	v_mfma_f32_16x16x16_bf16 v[8:11], v[154:155], v[34:35], v[8:11]
	v_pk_mul_f32 v[2:3], v[2:3], v[142:143]
	v_pk_mul_f32 v[0:1], v[0:1], v[140:141]
	v_mfma_f32_16x16x16_bf16 v[4:7], v[156:157], v[34:35], v[4:7]
	s_nop 1
	v_mfma_f32_16x16x16_bf16 v[0:3], v[158:159], v[34:35], v[0:3]
	ds_read_b128 v[112:115], v49 offset:1536
	ds_read_b64 v[144:145], v47 offset:96
	ds_read_b128 v[116:119], v49 offset:1600
	ds_read_b64 v[146:147], v47 offset:2400
	ds_read_b128 v[120:123], v49 offset:1664
	ds_read_b64 v[148:149], v47 offset:4704
	ds_read_b128 v[124:127], v49 offset:1728
	ds_read_b64 v[150:151], v47 offset:7008
	v_cvt_pk_bf16_f32 v84, v28, v29
	v_cvt_pk_bf16_f32 v85, v30, v31
	v_cvt_pk_bf16_f32 v86, v24, v25
	v_cvt_pk_bf16_f32 v87, v26, v27
	s_waitcnt lgkmcnt(8)
	v_mfma_f32_16x16x16_bf16 v[50:53], v[62:63], v[60:61], 0
	v_cvt_pk_bf16_f32 v88, v20, v21
	v_cvt_pk_bf16_f32 v89, v22, v23
	v_mfma_f32_16x16x16_bf16 v[50:53], v[68:69], v[84:85], v[50:53]
	v_mfma_f32_16x16x16_bf16 v[54:57], v[70:71], v[86:87], 0
	v_cvt_pk_bf16_f32 v90, v16, v17
	v_cvt_pk_bf16_f32 v91, v18, v19
	ds_read_b128 v[128:131], v49 offset:1792
	ds_read_b64 v[152:153], v47 offset:9312
	v_mfma_f32_16x16x16_bf16 v[50:53], v[72:73], v[88:89], v[50:53]
	v_cvt_pk_bf16_f32 v92, v12, v13
	v_cvt_pk_bf16_f32 v93, v14, v15
	ds_read_b128 v[132:135], v49 offset:1856
	ds_read_b64 v[154:155], v47 offset:11616
	v_mfma_f32_16x16x16_bf16 v[54:57], v[74:75], v[90:91], v[54:57]
	v_cvt_pk_bf16_f32 v94, v8, v9
	v_cvt_pk_bf16_f32 v95, v10, v11
	ds_read_b128 v[136:139], v49 offset:1920
	ds_read_b64 v[156:157], v47 offset:13920
	v_mfma_f32_16x16x16_bf16 v[50:53], v[76:77], v[92:93], v[50:53]
	v_cvt_pk_bf16_f32 v100, v4, v5
	v_cvt_pk_bf16_f32 v101, v6, v7
	ds_read_b128 v[140:143], v49 offset:1984
	ds_read_b64 v[158:159], v47 offset:16224
	v_mfma_f32_16x16x16_bf16 v[54:57], v[78:79], v[94:95], v[54:57]
	v_cvt_pk_bf16_f32 v102, v0, v1
	v_cvt_pk_bf16_f32 v103, v2, v3
	v_mfma_f32_16x16x16_bf16 v[50:53], v[80:81], v[100:101], v[50:53]
	s_nop 0
	v_mfma_f32_16x16x16_bf16 v[54:57], v[82:83], v[102:103], v[54:57]
	s_nop 7
	v_pk_add_f32 v[52:53], v[52:53], v[56:57]
	v_pk_add_f32 v[50:51], v[50:51], v[54:55]
	v_cvt_pk_bf16_f32 v59, v52, v53
	v_cvt_pk_bf16_f32 v58, v50, v51
	global_store_short v160, v58, s[14:15]
	global_store_short_d16_hi v161, v58, s[14:15]
	global_store_short v162, v59, s[14:15]
	global_store_short_d16_hi v163, v59, s[14:15]
	v_add_u32_e32 v160, s13, v160
	v_add_u32_e32 v161, s13, v161
	v_add_u32_e32 v162, s13, v162
	v_add_u32_e32 v163, s13, v163
	s_waitcnt lgkmcnt(0)
	v_pk_mul_f32 v[30:31], v[30:31], v[114:115]
	v_pk_mul_f32 v[28:29], v[28:29], v[112:113]
	v_pk_mul_f32 v[26:27], v[26:27], v[118:119]
	v_pk_mul_f32 v[24:25], v[24:25], v[116:117]
	v_mfma_f32_16x16x16_bf16 v[28:31], v[144:145], v[60:61], v[28:31]
	v_pk_mul_f32 v[22:23], v[22:23], v[122:123]
	v_pk_mul_f32 v[20:21], v[20:21], v[120:121]
	v_mfma_f32_16x16x16_bf16 v[24:27], v[146:147], v[60:61], v[24:27]
	v_pk_mul_f32 v[18:19], v[18:19], v[126:127]
	v_pk_mul_f32 v[16:17], v[16:17], v[124:125]
	v_mfma_f32_16x16x16_bf16 v[20:23], v[148:149], v[60:61], v[20:23]
	v_pk_mul_f32 v[14:15], v[14:15], v[130:131]
	v_pk_mul_f32 v[12:13], v[12:13], v[128:129]
	v_mfma_f32_16x16x16_bf16 v[16:19], v[150:151], v[60:61], v[16:19]
	v_pk_mul_f32 v[10:11], v[10:11], v[134:135]
	v_pk_mul_f32 v[8:9], v[8:9], v[132:133]
	v_mfma_f32_16x16x16_bf16 v[12:15], v[152:153], v[60:61], v[12:15]
	v_pk_mul_f32 v[6:7], v[6:7], v[138:139]
	v_pk_mul_f32 v[4:5], v[4:5], v[136:137]
	v_mfma_f32_16x16x16_bf16 v[8:11], v[154:155], v[60:61], v[8:11]
	v_pk_mul_f32 v[2:3], v[2:3], v[142:143]
	v_pk_mul_f32 v[0:1], v[0:1], v[140:141]
	v_mfma_f32_16x16x16_bf16 v[4:7], v[156:157], v[60:61], v[4:7]
	s_nop 1
	v_mfma_f32_16x16x16_bf16 v[0:3], v[158:159], v[60:61], v[0:3]
	s_add_i32 s0, s0, 1
	s_cmpk_lg_i32 s0, 0x81
	s_barrier
	s_cbranch_scc1 .Lhc_stage
	s_branch .LBB0_152

.LBB0_221:
	s_waitcnt vmcnt(63)
	v_lshlrev_b32_e32 v4, 16, v29
	v_and_b32_e32 v5, 0xffff0000, v29
	v_sub_f32_e32 v0, 1.0, v4
	v_max_f32_e32 v162, 0xda24260, v0
	v_sub_f32_e32 v0, 1.0, v5
	v_max_f32_e32 v163, 0xda24260, v0
	v_rcp_f32_e32 v164, v162
	v_rcp_f32_e32 v165, v163
	s_waitcnt vmcnt(63)
	v_lshlrev_b32_e32 v8, 16, v33
	v_and_b32_e32 v9, 0xffff0000, v33
	s_waitcnt vmcnt(63)
	v_lshlrev_b32_e32 v14, 16, v36
	v_pk_mul_f32 v[164:165], v[164:165], v[4:5]
	v_lshlrev_b32_e32 v4, 16, v30
	v_and_b32_e32 v5, 0xffff0000, v30
	v_pk_mul_f32 v[4:5], v[162:163], v[4:5]
	v_add_u32_e32 v166, v96, v106
	v_cvt_pk_bf16_f32 v157, v4, v5
	v_sub_f32_e32 v4, 1.0, v8
	v_sub_f32_e32 v5, 1.0, v9
	v_mul_f32_e32 v4, v162, v4
	v_max_f32_e32 v162, 0xda24260, v4
	v_mul_f32_e32 v4, v163, v5
	v_max_f32_e32 v163, 0xda24260, v4
	v_rcp_f32_e32 v4, v162
	v_rcp_f32_e32 v5, v163
	v_cvt_pk_bf16_f32 v167, v164, v165
	v_and_b32_e32 v15, 0xffff0000, v36
	ds_write2st64_b32 v166, v157, v167 offset1:68
	v_pk_mul_f32 v[4:5], v[4:5], v[8:9]
	v_lshlrev_b32_e32 v8, 16, v34
	v_and_b32_e32 v9, 0xffff0000, v34
	v_pk_mul_f32 v[8:9], v[162:163], v[8:9]
	v_cvt_pk_bf16_f32 v168, v4, v5
	v_cvt_pk_bf16_f32 v157, v8, v9
	v_sub_f32_e32 v8, 1.0, v14
	v_sub_f32_e32 v9, 1.0, v15
	v_mul_f32_e32 v8, v8, v162
	v_max_f32_e32 v162, 0xda24260, v8
	v_mul_f32_e32 v8, v9, v163
	v_max_f32_e32 v163, 0xda24260, v8
	v_rcp_f32_e32 v166, v162
	v_rcp_f32_e32 v167, v163
	v_mov_b32_e32 v8, v164
	v_mov_b32_e32 v9, v4
	v_mov_b32_e32 v4, v165
	v_pk_mul_f32 v[164:165], v[166:167], v[14:15]
	s_waitcnt vmcnt(63)
	v_lshlrev_b32_e32 v14, 16, v37
	v_and_b32_e32 v15, 0xffff0000, v37
	v_pk_mul_f32 v[14:15], v[162:163], v[14:15]
	s_waitcnt vmcnt(63)
	v_lshlrev_b32_e32 v18, 16, v39
	v_cvt_pk_bf16_f32 v14, v14, v15
	v_and_b32_e32 v19, 0xffff0000, v39
	ds_write2_b32 v112, v157, v14 offset1:68
	v_sub_f32_e32 v14, 1.0, v18
	v_sub_f32_e32 v15, 1.0, v19
	v_mul_f32_e32 v14, v14, v162
	v_max_f32_e32 v162, 0xda24260, v14
	v_mul_f32_e32 v14, v15, v163
	v_max_f32_e32 v163, 0xda24260, v14
	v_rcp_f32_e32 v14, v162
	v_rcp_f32_e32 v15, v163
	s_waitcnt vmcnt(63)
	v_lshlrev_b32_e32 v22, 16, v42
	v_cvt_pk_bf16_f32 v157, v164, v165
	v_add_u32_e32 v169, 0x4400, v112
	v_pk_mul_f32 v[14:15], v[14:15], v[18:19]
	v_lshlrev_b32_e32 v18, 16, v40
	v_and_b32_e32 v19, 0xffff0000, v40
	v_pk_mul_f32 v[18:19], v[162:163], v[18:19]
	v_and_b32_e32 v23, 0xffff0000, v42
	ds_write2_b32 v169, v168, v157 offset1:68
	v_cvt_pk_bf16_f32 v157, v18, v19
	v_sub_f32_e32 v18, 1.0, v22
	v_sub_f32_e32 v19, 1.0, v23
	v_mul_f32_e32 v18, v18, v162
	v_max_f32_e32 v162, 0xda24260, v18
	v_mul_f32_e32 v18, v19, v163
	v_max_f32_e32 v163, 0xda24260, v18
	v_rcp_f32_e32 v166, v162
	v_rcp_f32_e32 v167, v163
	v_cvt_pk_bf16_f32 v168, v14, v15
	v_mov_b32_e32 v18, v164
	v_mov_b32_e32 v19, v14
	v_mov_b32_e32 v14, v165
	v_pk_mul_f32 v[164:165], v[166:167], v[22:23]
	s_waitcnt vmcnt(63)
	v_lshlrev_b32_e32 v22, 16, v43
	v_and_b32_e32 v23, 0xffff0000, v43
	s_waitcnt vmcnt(63)
	v_lshlrev_b32_e32 v26, 16, v45
	v_pk_mul_f32 v[22:23], v[162:163], v[22:23]
	v_and_b32_e32 v27, 0xffff0000, v45
	v_cvt_pk_bf16_f32 v166, v22, v23
	v_sub_f32_e32 v22, 1.0, v26
	v_sub_f32_e32 v23, 1.0, v27
	v_mul_f32_e32 v22, v22, v162
	v_max_f32_e32 v162, 0xda24260, v22
	v_mul_f32_e32 v22, v23, v163
	v_max_f32_e32 v163, 0xda24260, v22
	v_rcp_f32_e32 v22, v162
	v_rcp_f32_e32 v23, v163
	s_waitcnt vmcnt(63)
	v_lshlrev_b32_e32 v158, 16, v48
	ds_write2_b32 v112, v157, v166 offset0:136 offset1:204
	v_cvt_pk_bf16_f32 v157, v164, v165
	v_pk_mul_f32 v[22:23], v[22:23], v[26:27]
	v_lshlrev_b32_e32 v26, 16, v46
	v_and_b32_e32 v27, 0xffff0000, v46
	v_pk_mul_f32 v[26:27], v[162:163], v[26:27]
	v_and_b32_e32 v159, 0xffff0000, v48
	ds_write2_b32 v169, v168, v157 offset0:136 offset1:204
	v_cvt_pk_bf16_f32 v157, v26, v27
	v_sub_f32_e32 v26, 1.0, v158
	v_sub_f32_e32 v27, 1.0, v159
	v_mul_f32_e32 v26, v26, v162
	v_max_f32_e32 v162, 0xda24260, v26
	v_mul_f32_e32 v26, v27, v163
	v_cvt_pk_bf16_f32 v168, v22, v23
	v_max_f32_e32 v163, 0xda24260, v26
	v_mov_b32_e32 v26, v164
	v_mov_b32_e32 v27, v22
	v_mov_b32_e32 v22, v165
	s_waitcnt vmcnt(63)
	v_lshlrev_b32_e32 v164, 16, v49
	v_and_b32_e32 v165, 0xffff0000, v49
	v_pk_mul_f32 v[164:165], v[162:163], v[164:165]
	s_waitcnt vmcnt(63)
	v_lshlrev_b32_e32 v160, 16, v51
	v_cvt_pk_bf16_f32 v164, v164, v165
	v_add_u32_e32 v169, 0x400, v112
	v_and_b32_e32 v161, 0xffff0000, v51
	ds_write2_b32 v169, v157, v164 offset0:16 offset1:84
	v_sub_f32_e32 v157, 1.0, v160
	v_sub_f32_e32 v164, 1.0, v161
	v_mul_f32_e32 v157, v157, v162
	v_rcp_f32_e32 v166, v162
	v_max_f32_e32 v162, 0xda24260, v157
	v_mul_f32_e32 v157, v164, v163
	v_rcp_f32_e32 v167, v163
	v_max_f32_e32 v163, 0xda24260, v157
	v_rcp_f32_e32 v164, v162
	v_rcp_f32_e32 v165, v163
	v_pk_mul_f32 v[158:159], v[166:167], v[158:159]
	s_waitcnt vmcnt(63)
	v_lshlrev_b32_e32 v24, 16, v57
	v_and_b32_e32 v25, 0xffff0000, v57
	v_pk_mul_f32 v[160:161], v[164:165], v[160:161]
	v_lshlrev_b32_e32 v164, 16, v52
	v_and_b32_e32 v165, 0xffff0000, v52
	v_cvt_pk_bf16_f32 v157, v158, v159
	v_add_u32_e32 v170, 0x4800, v112
	v_pk_mul_f32 v[164:165], v[162:163], v[164:165]
	ds_write2_b32 v170, v168, v157 offset0:16 offset1:84
	v_cvt_pk_bf16_f32 v157, v164, v165
	v_sub_f32_e32 v164, 1.0, v24
	v_sub_f32_e32 v165, 1.0, v25
	v_mul_f32_e32 v162, v164, v162
	v_mul_f32_e32 v163, v165, v163
	v_max_f32_e32 v162, 0xda24260, v162
	v_max_f32_e32 v163, 0xda24260, v163
	v_rcp_f32_e32 v164, v162
	v_rcp_f32_e32 v165, v163
	v_cvt_pk_bf16_f32 v168, v160, v161
	v_mov_b32_e32 v166, v158
	v_mov_b32_e32 v167, v160
	v_mov_b32_e32 v160, v159
	s_waitcnt vmcnt(63)
	v_lshlrev_b32_e32 v158, 16, v59
	v_and_b32_e32 v159, 0xffff0000, v59
	s_waitcnt vmcnt(63)
	v_lshlrev_b32_e32 v20, 16, v63
	v_and_b32_e32 v21, 0xffff0000, v63
	v_pk_mul_f32 v[158:159], v[162:163], v[158:159]
	v_pk_mul_f32 v[24:25], v[164:165], v[24:25]
	v_cvt_pk_bf16_f32 v164, v158, v159
	v_sub_f32_e32 v158, 1.0, v20
	v_sub_f32_e32 v159, 1.0, v21
	v_mul_f32_e32 v158, v158, v162
	v_mul_f32_e32 v159, v159, v163
	v_max_f32_e32 v158, 0xda24260, v158
	v_max_f32_e32 v159, 0xda24260, v159
	v_rcp_f32_e32 v162, v158
	v_rcp_f32_e32 v163, v159
	s_waitcnt vmcnt(63)
	v_lshlrev_b32_e32 v16, 16, v69
	v_and_b32_e32 v17, 0xffff0000, v69
	ds_write2_b32 v169, v157, v164 offset0:152 offset1:220
	v_pk_mul_f32 v[20:21], v[162:163], v[20:21]
	v_lshlrev_b32_e32 v162, 16, v64
	v_and_b32_e32 v163, 0xffff0000, v64
	v_cvt_pk_bf16_f32 v157, v24, v25
	v_pk_mul_f32 v[162:163], v[158:159], v[162:163]
	ds_write2_b32 v170, v168, v157 offset0:152 offset1:220
	v_cvt_pk_bf16_f32 v157, v162, v163
	v_sub_f32_e32 v162, 1.0, v16
	v_sub_f32_e32 v163, 1.0, v17
	v_mul_f32_e32 v158, v162, v158
	v_mul_f32_e32 v159, v163, v159
	v_cvt_pk_bf16_f32 v168, v20, v21
	v_max_f32_e32 v158, 0xda24260, v158
	v_max_f32_e32 v159, 0xda24260, v159
	v_mov_b32_e32 v164, v24
	v_mov_b32_e32 v165, v20
	v_mov_b32_e32 v20, v25
	s_waitcnt vmcnt(63)
	v_lshlrev_b32_e32 v24, 16, v71
	v_and_b32_e32 v25, 0xffff0000, v71
	v_pk_mul_f32 v[24:25], v[158:159], v[24:25]
	s_waitcnt vmcnt(62)
	v_lshlrev_b32_e32 v12, 16, v75
	v_and_b32_e32 v13, 0xffff0000, v75
	v_cvt_pk_bf16_f32 v24, v24, v25
	v_add_u32_e32 v169, 0x800, v112
	ds_write2_b32 v169, v157, v24 offset0:32 offset1:100
	v_sub_f32_e32 v24, 1.0, v12
	v_sub_f32_e32 v25, 1.0, v13
	v_mul_f32_e32 v24, v24, v158
	v_mul_f32_e32 v25, v25, v159
	v_max_f32_e32 v24, 0xda24260, v24
	v_max_f32_e32 v25, 0xda24260, v25
	v_rcp_f32_e32 v162, v158
	v_rcp_f32_e32 v163, v159
	v_rcp_f32_e32 v158, v24
	v_rcp_f32_e32 v159, v25
	s_waitcnt vmcnt(59)
	v_lshlrev_b32_e32 v10, 16, v81
	v_pk_mul_f32 v[16:17], v[162:163], v[16:17]
	v_and_b32_e32 v11, 0xffff0000, v81
	v_pk_mul_f32 v[158:159], v[158:159], v[12:13]
	v_lshlrev_b32_e32 v12, 16, v76
	v_and_b32_e32 v13, 0xffff0000, v76
	v_cvt_pk_bf16_f32 v157, v16, v17
	v_add_u32_e32 v170, 0x4c00, v112
	v_pk_mul_f32 v[12:13], v[24:25], v[12:13]
	ds_write2_b32 v170, v168, v157 offset0:32 offset1:100
	v_cvt_pk_bf16_f32 v157, v12, v13
	v_sub_f32_e32 v12, 1.0, v10
	v_sub_f32_e32 v13, 1.0, v11
	v_mul_f32_e32 v12, v12, v24
	v_mul_f32_e32 v13, v13, v25
	v_max_f32_e32 v12, 0xda24260, v12
	v_max_f32_e32 v13, 0xda24260, v13
	v_rcp_f32_e32 v24, v12
	v_rcp_f32_e32 v25, v13
	v_cvt_pk_bf16_f32 v168, v158, v159
	v_mov_b32_e32 v162, v16
	v_mov_b32_e32 v163, v158
	v_mov_b32_e32 v158, v17
	s_waitcnt vmcnt(58)
	v_lshlrev_b32_e32 v16, 16, v83
	v_and_b32_e32 v17, 0xffff0000, v83
	s_waitcnt vmcnt(56)
	v_lshlrev_b32_e32 v6, 16, v87
	v_and_b32_e32 v7, 0xffff0000, v87
	v_pk_mul_f32 v[16:17], v[12:13], v[16:17]
	v_pk_mul_f32 v[10:11], v[24:25], v[10:11]
	v_cvt_pk_bf16_f32 v24, v16, v17
	v_sub_f32_e32 v16, 1.0, v6
	v_sub_f32_e32 v17, 1.0, v7
	v_mul_f32_e32 v12, v16, v12
	v_mul_f32_e32 v13, v17, v13
	v_max_f32_e32 v12, 0xda24260, v12
	v_max_f32_e32 v13, 0xda24260, v13
	v_rcp_f32_e32 v16, v12
	v_rcp_f32_e32 v17, v13
	ds_write2_b32 v169, v157, v24 offset0:168 offset1:236
	v_cvt_pk_bf16_f32 v24, v10, v11
	ds_write2_b32 v170, v168, v24 offset0:168 offset1:236
	v_pk_mul_f32 v[24:25], v[16:17], v[6:7]
	s_waitcnt vmcnt(55)
	v_lshlrev_b32_e32 v6, 16, v88
	v_and_b32_e32 v7, 0xffff0000, v88
	s_waitcnt vmcnt(53)
	v_lshlrev_b32_e32 v2, 16, v93
	v_and_b32_e32 v3, 0xffff0000, v93
	v_pk_mul_f32 v[6:7], v[12:13], v[6:7]
	s_waitcnt vmcnt(50)
	v_lshlrev_b32_e32 v0, 16, v107
	v_cvt_pk_bf16_f32 v16, v6, v7
	v_sub_f32_e32 v6, 1.0, v2
	v_sub_f32_e32 v7, 1.0, v3
	v_mul_f32_e32 v6, v6, v12
	v_mul_f32_e32 v7, v7, v13
	v_max_f32_e32 v6, 0xda24260, v6
	v_max_f32_e32 v7, 0xda24260, v7
	v_rcp_f32_e32 v12, v6
	v_rcp_f32_e32 v13, v7
	v_and_b32_e32 v1, 0xffff0000, v107
	v_cvt_pk_bf16_f32 v17, v24, v25
	v_mov_b32_e32 v168, v10
	v_pk_mul_f32 v[170:171], v[12:13], v[2:3]
	v_lshlrev_b32_e32 v2, 16, v95
	v_and_b32_e32 v3, 0xffff0000, v95
	v_pk_mul_f32 v[2:3], v[6:7], v[2:3]
	v_mov_b32_e32 v169, v24
	v_cvt_pk_bf16_f32 v2, v2, v3
	v_add_u32_e32 v3, 0xc00, v112
	ds_write2_b32 v3, v16, v2 offset0:48 offset1:116
	v_cvt_pk_bf16_f32 v2, v170, v171
	v_add_u32_e32 v3, 0x5000, v112
	ds_write2_b32 v3, v17, v2 offset0:48 offset1:116
	v_sub_f32_e32 v2, 1.0, v0
	v_sub_f32_e32 v3, 1.0, v1
	v_mul_f32_e32 v2, v2, v6
	v_mul_f32_e32 v3, v3, v7
	v_max_f32_e32 v2, 0xda24260, v2
	v_max_f32_e32 v172, 0xda24260, v3
	v_mov_b32_e32 v24, v11
	v_pk_mul_f32 v[6:7], v[8:9], v[2:3] op_sel_hi:[1,0]
	v_pk_mul_f32 v[8:9], v[4:5], v[172:173] op_sel_hi:[1,0]
	v_pk_mul_f32 v[10:11], v[14:15], v[172:173] op_sel_hi:[1,0]
	v_cvt_pk_bf16_f32 v8, v8, v9
	v_cvt_pk_bf16_f32 v9, v10, v11
	v_pk_mul_f32 v[10:11], v[22:23], v[172:173] op_sel_hi:[1,0]
	v_pk_mul_f32 v[14:15], v[160:161], v[172:173] op_sel_hi:[1,0]
	v_cvt_pk_bf16_f32 v10, v10, v11
	v_cvt_pk_bf16_f32 v11, v14, v15
	v_pk_mul_f32 v[14:15], v[20:21], v[172:173] op_sel_hi:[1,0]
	v_rcp_f32_e32 v20, v2
	v_rcp_f32_e32 v21, v172
	v_cvt_pk_bf16_f32 v4, v6, v7
	v_pk_mul_f32 v[6:7], v[18:19], v[2:3] op_sel_hi:[1,0]
	v_pk_mul_f32 v[12:13], v[166:167], v[2:3] op_sel_hi:[1,0]
	v_cvt_pk_bf16_f32 v5, v6, v7
	v_pk_mul_f32 v[6:7], v[26:27], v[2:3] op_sel_hi:[1,0]
	v_cvt_pk_bf16_f32 v16, v14, v15
	v_cvt_pk_bf16_f32 v6, v6, v7
	v_cvt_pk_bf16_f32 v7, v12, v13
	v_pk_mul_f32 v[12:13], v[164:165], v[2:3] op_sel_hi:[1,0]
	v_pk_mul_f32 v[14:15], v[162:163], v[2:3] op_sel_hi:[1,0]
	v_cvt_pk_bf16_f32 v12, v12, v13
	v_cvt_pk_bf16_f32 v13, v14, v15
	v_pk_mul_f32 v[14:15], v[168:169], v[2:3] op_sel_hi:[1,0]
	v_pk_mul_f32 v[0:1], v[20:21], v[0:1]
	s_waitcnt vmcnt(48)
	v_lshlrev_b32_e32 v20, 16, v108
	v_and_b32_e32 v21, 0xffff0000, v108
	v_mov_b32_e32 v3, v172
	v_pk_mul_f32 v[20:21], v[2:3], v[20:21]
	v_cvt_pk_bf16_f32 v14, v14, v15
	v_cvt_pk_bf16_f32 v15, v20, v21
	v_pk_mul_f32 v[18:19], v[158:159], v[172:173] op_sel_hi:[1,0]
	ds_write_b32 v112, v15 offset:3808
	v_cvt_pk_bf16_f32 v15, v0, v1
	v_mov_b32_e32 v21, v0
	v_mov_b32_e32 v0, v171
	v_cvt_pk_bf16_f32 v17, v18, v19
	v_pk_mul_f32 v[18:19], v[24:25], v[172:173] op_sel_hi:[1,0]
	v_mov_b32_e32 v20, v170
	v_pk_mul_f32 v[0:1], v[172:173], v[0:1] op_sel_hi:[0,1]
	v_cvt_pk_bf16_f32 v18, v18, v19
	v_pk_mul_f32 v[20:21], v[2:3], v[20:21] op_sel_hi:[0,1]
	v_cvt_pk_bf16_f32 v19, v0, v1
	v_add_u32_e32 v0, v98, v100
	ds_write_b32 v112, v15 offset:21216
	v_cvt_pk_bf16_f32 v15, v20, v21
	ds_write_b128 v0, v[4:7] offset:34816
	ds_write_b128 v0, v[12:15] offset:34832
	ds_write_b128 v0, v[8:11] offset:34960
	ds_write_b128 v0, v[16:19] offset:34976
	s_and_saveexec_b64 s[14:15], s[38:39]
	s_cbranch_execz .LBB0_223
	v_lshrrev_b32_e32 v0, 16, v31
	v_and_or_b32 v4, v32, s33, v0
	v_lshrrev_b32_e32 v0, 16, v35
	v_and_or_b32 v5, v38, s33, v0
	v_lshrrev_b32_e32 v0, 16, v41
	v_and_or_b32 v6, v44, s33, v0
	v_lshrrev_b32_e32 v0, 16, v47
	v_and_or_b32 v7, v50, s33, v0
	v_lshrrev_b32_e32 v0, 16, v56
	v_and_or_b32 v8, v62, s33, v0
	v_lshrrev_b32_e32 v0, 16, v68
	v_and_or_b32 v9, v74, s33, v0
	v_lshrrev_b32_e32 v0, 16, v80
	v_and_or_b32 v10, v86, s33, v0
	v_lshrrev_b32_e32 v0, 16, v92
	v_and_or_b32 v11, v105, s33, v0
	v_and_b32_e32 v0, 0xffff, v31
	v_lshl_or_b32 v12, v32, 16, v0
	v_and_b32_e32 v0, 0xffff, v35
	v_lshl_or_b32 v13, v38, 16, v0
	v_and_b32_e32 v0, 0xffff, v41
	v_lshl_or_b32 v14, v44, 16, v0
	v_and_b32_e32 v0, 0xffff, v47
	v_lshl_or_b32 v15, v50, 16, v0
	v_and_b32_e32 v0, 0xffff, v56
	v_lshl_or_b32 v16, v62, 16, v0
	v_and_b32_e32 v0, 0xffff, v68
	v_lshl_or_b32 v17, v74, 16, v0
	v_and_b32_e32 v0, 0xffff, v80
	v_lshl_or_b32 v18, v86, 16, v0
	v_and_b32_e32 v0, 0xffff, v92
	v_lshl_or_b32 v19, v105, 16, v0
	ds_write_b128 v113, v[12:15] offset:53248
	ds_write_b128 v113, v[16:19] offset:53264
	ds_write_b128 v113, v[4:7] offset:53392
	ds_write_b128 v113, v[8:11] offset:53408
.LBB0_223:
	s_or_b64 exec, exec, s[14:15]
	ds_write_b64 v134, v[2:3] offset:62464
	v_add_u32_e32 v157, v101, v102
	ds_read_b128 v[0:3], v157 offset:17408
	ds_read_b128 v[4:7], v157
	s_cmpk_gt_u32 s18, 0x7d
	s_cselect_b64 s[14:15], -1, 0
	s_and_b64 vcc, exec, s[14:15]
	s_waitcnt lgkmcnt(0)
	v_mfma_f32_16x16x32_bf16 v[0:3], v[0:3], v[4:7], 0
	ds_read_b128 v[4:7], v157 offset:17472
	ds_read_b128 v[8:11], v157 offset:64
	s_waitcnt lgkmcnt(0)
	v_mfma_f32_16x16x32_bf16 v[0:3], v[4:7], v[8:11], v[0:3]
	ds_read_b128 v[4:7], v157 offset:17536
	ds_read_b128 v[8:11], v157 offset:128
	s_waitcnt lgkmcnt(0)
	v_mfma_f32_16x16x32_bf16 v[0:3], v[4:7], v[8:11], v[0:3]
	ds_read_b128 v[4:7], v157 offset:17600
	ds_read_b128 v[8:11], v157 offset:192
	s_waitcnt lgkmcnt(0)
	v_mfma_f32_16x16x32_bf16 v[0:3], v[4:7], v[8:11], v[0:3]
	s_nop 7
	v_cndmask_b32_e64 v0, v0, 0, s[40:41]
	v_cndmask_b32_e64 v1, 0, v1, s[42:43]
	v_cndmask_b32_e64 v2, v2, 0, s[44:45]
	v_cndmask_b32_e64 v3, v3, 0, s[46:47]
	v_cvt_pk_bf16_f32 v0, v0, v1
	v_cvt_pk_bf16_f32 v1, v2, v3
	ds_write_b64 v135, v[0:1] offset:256
	s_cbranch_vccnz .Lh3_skipA
	v_add_u32_e32 v0, 0xffffffb1, v110
	v_add_u32_e32 v1, 0x4f, v111
	v_cndmask_b32_e64 v0, v1, v0, s[36:37]
	s_and_b64 s[16:17], s[36:37], exec
	s_movk_i32 s16, 0x1000
	s_cselect_b32 s16, s16, 0xfffff000
	v_add_u32_e32 v0, s4, v0
	v_lshlrev_b32_e32 v0, 12, v0
	v_lshl_or_b32 v0, v28, 1, v0
	global_load_dword v29, v0, s[12:13]
	global_load_dword v30, v0, s[0:1]
	global_load_dword v31, v0, s[10:11]
	v_add_u32_e32 v0, s16, v0
	global_load_dword v33, v0, s[12:13]
	global_load_dword v34, v0, s[0:1]
	global_load_dword v32, v0, s[10:11]
	v_add_u32_e32 v0, s16, v0
	global_load_dword v36, v0, s[12:13]
	global_load_dword v37, v0, s[0:1]
	global_load_dword v35, v0, s[10:11]
	v_add_u32_e32 v0, s16, v0
	global_load_dword v39, v0, s[12:13]
	global_load_dword v40, v0, s[0:1]
	global_load_dword v38, v0, s[10:11]
	v_add_u32_e32 v0, s16, v0
	global_load_dword v42, v0, s[12:13]
	global_load_dword v43, v0, s[0:1]
	global_load_dword v41, v0, s[10:11]
	v_add_u32_e32 v0, s16, v0
	global_load_dword v45, v0, s[12:13]
	global_load_dword v46, v0, s[0:1]
	global_load_dword v44, v0, s[10:11]
	v_add_u32_e32 v0, s16, v0
	global_load_dword v48, v0, s[12:13]
	global_load_dword v49, v0, s[0:1]
	global_load_dword v47, v0, s[10:11]
	v_add_u32_e32 v0, s16, v0
	global_load_dword v51, v0, s[12:13]
	global_load_dword v52, v0, s[0:1]
	global_load_dword v50, v0, s[10:11]
	v_add_u32_e32 v0, s16, v0
	global_load_dword v57, v0, s[12:13]
	global_load_dword v59, v0, s[0:1]
	global_load_dword v56, v0, s[10:11]
	v_add_u32_e32 v0, s16, v0
	global_load_dword v63, v0, s[12:13]
	global_load_dword v64, v0, s[0:1]
	global_load_dword v62, v0, s[10:11]
	v_add_u32_e32 v0, s16, v0
	global_load_dword v69, v0, s[12:13]
	global_load_dword v71, v0, s[0:1]
	global_load_dword v68, v0, s[10:11]
	v_add_u32_e32 v0, s16, v0
	global_load_dword v75, v0, s[12:13]
	global_load_dword v76, v0, s[0:1]
	global_load_dword v74, v0, s[10:11]
	v_add_u32_e32 v0, s16, v0
	global_load_dword v81, v0, s[12:13]
	global_load_dword v83, v0, s[0:1]
	global_load_dword v80, v0, s[10:11]
	v_add_u32_e32 v0, s16, v0
	global_load_dword v87, v0, s[12:13]
	global_load_dword v88, v0, s[0:1]
	global_load_dword v86, v0, s[10:11]
	v_add_u32_e32 v0, s16, v0
	global_load_dword v93, v0, s[12:13]
	global_load_dword v95, v0, s[0:1]
	global_load_dword v92, v0, s[10:11]
	v_add_u32_e32 v0, s16, v0
	global_load_dword v107, v0, s[12:13]
	global_load_dword v108, v0, s[0:1]
	global_load_dword v105, v0, s[10:11]
	s_branch .LBB0_257

.LBB0_257:
	s_waitcnt vmcnt(63)
	v_lshlrev_b32_e32 v4, 16, v54
	v_and_b32_e32 v5, 0xffff0000, v54
	v_sub_f32_e32 v0, 1.0, v4
	v_max_f32_e32 v162, 0xda24260, v0
	v_sub_f32_e32 v0, 1.0, v5
	v_max_f32_e32 v163, 0xda24260, v0
	v_rcp_f32_e32 v164, v162
	v_rcp_f32_e32 v165, v163
	s_waitcnt vmcnt(63)
	v_lshlrev_b32_e32 v10, 16, v60
	v_and_b32_e32 v11, 0xffff0000, v60
	v_add_u32_e32 v168, v104, v106
	v_pk_mul_f32 v[164:165], v[164:165], v[4:5]
	v_lshlrev_b32_e32 v4, 16, v55
	v_and_b32_e32 v5, 0xffff0000, v55
	v_pk_mul_f32 v[4:5], v[162:163], v[4:5]
	s_waitcnt lgkmcnt(0)
	v_cvt_pk_bf16_f32 v166, v4, v5
	v_sub_f32_e32 v4, 1.0, v10
	v_sub_f32_e32 v5, 1.0, v11
	v_mul_f32_e32 v4, v162, v4
	v_max_f32_e32 v162, 0xda24260, v4
	v_mul_f32_e32 v4, v163, v5
	v_max_f32_e32 v163, 0xda24260, v4
	v_rcp_f32_e32 v4, v162
	v_rcp_f32_e32 v5, v163
	s_barrier
	ds_write_b32 v168, v166 offset:64512
	v_pk_mul_f32 v[4:5], v[4:5], v[10:11]
	s_waitcnt vmcnt(63)
	v_lshlrev_b32_e32 v10, 16, v61
	v_and_b32_e32 v11, 0xffff0000, v61
	v_pk_mul_f32 v[10:11], v[162:163], v[10:11]
	v_cvt_pk_bf16_f32 v166, v164, v165
	v_cvt_pk_bf16_f32 v10, v10, v11
	s_waitcnt vmcnt(63)
	v_lshlrev_b32_e32 v14, 16, v66
	ds_write_b32 v114, v166
	ds_write_b32 v168, v10 offset:64784
	v_cvt_pk_bf16_f32 v10, v4, v5
	v_and_b32_e32 v15, 0xffff0000, v66
	ds_write_b32 v114, v10 offset:272
	v_sub_f32_e32 v10, 1.0, v14
	v_sub_f32_e32 v11, 1.0, v15
	v_mul_f32_e32 v10, v10, v162
	v_max_f32_e32 v162, 0xda24260, v10
	v_mul_f32_e32 v10, v11, v163
	v_max_f32_e32 v163, 0xda24260, v10
	v_rcp_f32_e32 v166, v162
	v_rcp_f32_e32 v167, v163
	v_mov_b32_e32 v10, v164
	v_mov_b32_e32 v11, v4
	v_mov_b32_e32 v4, v165
	v_pk_mul_f32 v[164:165], v[166:167], v[14:15]
	s_waitcnt vmcnt(63)
	v_lshlrev_b32_e32 v14, 16, v67
	v_and_b32_e32 v15, 0xffff0000, v67
	s_waitcnt vmcnt(63)
	v_lshlrev_b32_e32 v18, 16, v72
	v_pk_mul_f32 v[14:15], v[162:163], v[14:15]
	v_and_b32_e32 v19, 0xffff0000, v72
	v_cvt_pk_bf16_f32 v166, v14, v15
	v_sub_f32_e32 v14, 1.0, v18
	v_sub_f32_e32 v15, 1.0, v19
	v_mul_f32_e32 v14, v14, v162
	v_max_f32_e32 v162, 0xda24260, v14
	v_mul_f32_e32 v14, v15, v163
	v_max_f32_e32 v163, 0xda24260, v14
	v_rcp_f32_e32 v14, v162
	v_rcp_f32_e32 v15, v163
	ds_write_b32 v168, v166 offset:65056
	v_cvt_pk_bf16_f32 v166, v164, v165
	s_waitcnt vmcnt(63)
	v_lshlrev_b32_e32 v22, 16, v78
	v_pk_mul_f32 v[14:15], v[14:15], v[18:19]
	v_lshlrev_b32_e32 v18, 16, v73
	v_and_b32_e32 v19, 0xffff0000, v73
	v_pk_mul_f32 v[18:19], v[162:163], v[18:19]
	ds_write_b32 v114, v166 offset:544
	v_cvt_pk_bf16_f32 v18, v18, v19
	ds_write_b32 v168, v18 offset:65328
	v_cvt_pk_bf16_f32 v18, v14, v15
	v_and_b32_e32 v23, 0xffff0000, v78
	ds_write_b32 v114, v18 offset:816
	v_sub_f32_e32 v18, 1.0, v22
	v_sub_f32_e32 v19, 1.0, v23
	v_mul_f32_e32 v18, v18, v162
	v_max_f32_e32 v162, 0xda24260, v18
	v_mul_f32_e32 v18, v19, v163
	v_max_f32_e32 v163, 0xda24260, v18
	v_rcp_f32_e32 v166, v162
	v_rcp_f32_e32 v167, v163
	v_mov_b32_e32 v18, v164
	v_mov_b32_e32 v19, v14
	v_mov_b32_e32 v14, v165
	v_pk_mul_f32 v[164:165], v[166:167], v[22:23]
	s_waitcnt vmcnt(63)
	v_lshlrev_b32_e32 v22, 16, v79
	v_and_b32_e32 v23, 0xffff0000, v79
	s_waitcnt vmcnt(63)
	v_lshlrev_b32_e32 v26, 16, v84
	v_pk_mul_f32 v[22:23], v[162:163], v[22:23]
	v_and_b32_e32 v27, 0xffff0000, v84
	v_cvt_pk_bf16_f32 v166, v22, v23
	v_sub_f32_e32 v22, 1.0, v26
	v_sub_f32_e32 v23, 1.0, v27
	v_mul_f32_e32 v22, v22, v162
	v_max_f32_e32 v162, 0xda24260, v22
	v_mul_f32_e32 v22, v23, v163
	v_max_f32_e32 v163, 0xda24260, v22
	v_rcp_f32_e32 v22, v162
	v_rcp_f32_e32 v23, v163
	ds_write_b32 v115, v166 offset:64512
	v_cvt_pk_bf16_f32 v166, v164, v165
	s_waitcnt vmcnt(63)
	v_lshlrev_b32_e32 v158, 16, v90
	v_pk_mul_f32 v[22:23], v[22:23], v[26:27]
	v_lshlrev_b32_e32 v26, 16, v85
	v_and_b32_e32 v27, 0xffff0000, v85
	v_pk_mul_f32 v[26:27], v[162:163], v[26:27]
	ds_write_b32 v114, v166 offset:1088
	v_cvt_pk_bf16_f32 v26, v26, v27
	ds_write_b32 v116, v26 offset:64512
	v_cvt_pk_bf16_f32 v26, v22, v23
	v_and_b32_e32 v159, 0xffff0000, v90
	ds_write_b32 v114, v26 offset:1360
	v_sub_f32_e32 v26, 1.0, v158
	v_sub_f32_e32 v27, 1.0, v159
	v_mul_f32_e32 v26, v26, v162
	v_max_f32_e32 v162, 0xda24260, v26
	v_mul_f32_e32 v26, v27, v163
	v_max_f32_e32 v163, 0xda24260, v26
	v_rcp_f32_e32 v166, v162
	v_rcp_f32_e32 v167, v163
	v_mov_b32_e32 v26, v164
	v_mov_b32_e32 v27, v22
	v_mov_b32_e32 v22, v165
	s_waitcnt vmcnt(63)
	v_lshlrev_b32_e32 v164, 16, v91
	v_and_b32_e32 v165, 0xffff0000, v91
	s_waitcnt vmcnt(63)
	v_lshlrev_b32_e32 v160, 16, v99
	v_and_b32_e32 v161, 0xffff0000, v99
	v_pk_mul_f32 v[164:165], v[162:163], v[164:165]
	v_pk_mul_f32 v[158:159], v[166:167], v[158:159]
	v_cvt_pk_bf16_f32 v166, v164, v165
	v_sub_f32_e32 v164, 1.0, v160
	v_sub_f32_e32 v165, 1.0, v161
	v_mul_f32_e32 v162, v164, v162
	v_mul_f32_e32 v163, v165, v163
	v_max_f32_e32 v162, 0xda24260, v162
	v_max_f32_e32 v163, 0xda24260, v163
	v_rcp_f32_e32 v164, v162
	v_rcp_f32_e32 v165, v163
	ds_write_b32 v117, v166 offset:64512
	v_cvt_pk_bf16_f32 v166, v158, v159
	s_waitcnt vmcnt(63)
	v_lshlrev_b32_e32 v24, 16, v121
	v_pk_mul_f32 v[160:161], v[164:165], v[160:161]
	v_lshlrev_b32_e32 v164, 16, v103
	v_and_b32_e32 v165, 0xffff0000, v103
	v_pk_mul_f32 v[164:165], v[162:163], v[164:165]
	v_and_b32_e32 v25, 0xffff0000, v121
	v_cvt_pk_bf16_f32 v164, v164, v165
	ds_write_b32 v114, v166 offset:1632
	ds_write_b32 v118, v164 offset:64512
	v_cvt_pk_bf16_f32 v164, v160, v161
	ds_write_b32 v114, v164 offset:1904
	v_sub_f32_e32 v164, 1.0, v24
	v_sub_f32_e32 v165, 1.0, v25
	v_mul_f32_e32 v162, v164, v162
	v_mul_f32_e32 v163, v165, v163
	v_max_f32_e32 v162, 0xda24260, v162
	v_max_f32_e32 v163, 0xda24260, v163
	v_rcp_f32_e32 v164, v162
	v_rcp_f32_e32 v165, v163
	v_mov_b32_e32 v166, v158
	v_mov_b32_e32 v167, v160
	v_mov_b32_e32 v160, v159
	s_waitcnt vmcnt(63)
	v_lshlrev_b32_e32 v158, 16, v131
	v_and_b32_e32 v159, 0xffff0000, v131
	s_waitcnt vmcnt(63)
	v_lshlrev_b32_e32 v20, 16, v137
	v_and_b32_e32 v21, 0xffff0000, v137
	v_pk_mul_f32 v[158:159], v[162:163], v[158:159]
	v_pk_mul_f32 v[24:25], v[164:165], v[24:25]
	v_cvt_pk_bf16_f32 v164, v158, v159
	v_sub_f32_e32 v158, 1.0, v20
	v_sub_f32_e32 v159, 1.0, v21
	v_mul_f32_e32 v158, v158, v162
	v_mul_f32_e32 v159, v159, v163
	v_max_f32_e32 v158, 0xda24260, v158
	v_max_f32_e32 v159, 0xda24260, v159
	v_rcp_f32_e32 v162, v158
	v_rcp_f32_e32 v163, v159
	ds_write_b32 v119, v164 offset:64512
	v_cvt_pk_bf16_f32 v164, v24, v25
	s_waitcnt vmcnt(63)
	v_lshlrev_b32_e32 v16, 16, v140
	v_pk_mul_f32 v[20:21], v[162:163], v[20:21]
	v_lshlrev_b32_e32 v162, 16, v138
	v_and_b32_e32 v163, 0xffff0000, v138
	v_pk_mul_f32 v[162:163], v[158:159], v[162:163]
	v_and_b32_e32 v17, 0xffff0000, v140
	v_cvt_pk_bf16_f32 v162, v162, v163
	ds_write_b32 v114, v164 offset:2176
	ds_write_b32 v120, v162 offset:64512
	v_cvt_pk_bf16_f32 v162, v20, v21
	ds_write_b32 v114, v162 offset:2448
	v_sub_f32_e32 v162, 1.0, v16
	v_sub_f32_e32 v163, 1.0, v17
	v_mul_f32_e32 v158, v162, v158
	v_mul_f32_e32 v159, v163, v159
	v_max_f32_e32 v158, 0xda24260, v158
	v_max_f32_e32 v159, 0xda24260, v159
	v_rcp_f32_e32 v162, v158
	v_rcp_f32_e32 v163, v159
	v_mov_b32_e32 v164, v24
	v_mov_b32_e32 v165, v20
	v_mov_b32_e32 v20, v25
	s_waitcnt vmcnt(63)
	v_lshlrev_b32_e32 v24, 16, v141
	v_and_b32_e32 v25, 0xffff0000, v141
	s_waitcnt vmcnt(62)
	v_lshlrev_b32_e32 v12, 16, v143
	v_and_b32_e32 v13, 0xffff0000, v143
	v_pk_mul_f32 v[24:25], v[158:159], v[24:25]
	v_pk_mul_f32 v[16:17], v[162:163], v[16:17]
	v_cvt_pk_bf16_f32 v162, v24, v25
	v_sub_f32_e32 v24, 1.0, v12
	v_sub_f32_e32 v25, 1.0, v13
	v_mul_f32_e32 v24, v24, v158
	v_mul_f32_e32 v25, v25, v159
	v_max_f32_e32 v24, 0xda24260, v24
	v_max_f32_e32 v25, 0xda24260, v25
	v_rcp_f32_e32 v158, v24
	v_rcp_f32_e32 v159, v25
	ds_write_b32 v122, v162 offset:64512
	v_cvt_pk_bf16_f32 v162, v16, v17
	s_waitcnt vmcnt(59)
	v_lshlrev_b32_e32 v8, 16, v146
	v_pk_mul_f32 v[158:159], v[158:159], v[12:13]
	v_lshlrev_b32_e32 v12, 16, v144
	v_and_b32_e32 v13, 0xffff0000, v144
	v_pk_mul_f32 v[12:13], v[24:25], v[12:13]
	v_and_b32_e32 v9, 0xffff0000, v146
	v_cvt_pk_bf16_f32 v12, v12, v13
	ds_write_b32 v114, v162 offset:2720
	ds_write_b32 v123, v12 offset:64512
	v_cvt_pk_bf16_f32 v12, v158, v159
	ds_write_b32 v114, v12 offset:2992
	v_sub_f32_e32 v12, 1.0, v8
	v_sub_f32_e32 v13, 1.0, v9
	v_mul_f32_e32 v12, v12, v24
	v_mul_f32_e32 v13, v13, v25
	v_max_f32_e32 v12, 0xda24260, v12
	v_max_f32_e32 v13, 0xda24260, v13
	v_rcp_f32_e32 v24, v12
	v_rcp_f32_e32 v25, v13
	v_mov_b32_e32 v162, v16
	v_mov_b32_e32 v163, v158
	v_mov_b32_e32 v158, v17
	s_waitcnt vmcnt(58)
	v_lshlrev_b32_e32 v16, 16, v147
	v_and_b32_e32 v17, 0xffff0000, v147
	s_waitcnt vmcnt(56)
	v_lshlrev_b32_e32 v6, 16, v149
	v_and_b32_e32 v7, 0xffff0000, v149
	v_pk_mul_f32 v[16:17], v[12:13], v[16:17]
	v_pk_mul_f32 v[8:9], v[24:25], v[8:9]
	v_cvt_pk_bf16_f32 v24, v16, v17
	v_sub_f32_e32 v16, 1.0, v6
	v_sub_f32_e32 v17, 1.0, v7
	v_mul_f32_e32 v12, v16, v12
	v_mul_f32_e32 v13, v17, v13
	v_max_f32_e32 v12, 0xda24260, v12
	v_max_f32_e32 v13, 0xda24260, v13
	v_rcp_f32_e32 v16, v12
	v_rcp_f32_e32 v17, v13
	ds_write_b32 v124, v24 offset:64512
	v_cvt_pk_bf16_f32 v24, v8, v9
	ds_write_b32 v114, v24 offset:3264
	v_pk_mul_f32 v[24:25], v[16:17], v[6:7]
	s_waitcnt vmcnt(55)
	v_lshlrev_b32_e32 v6, 16, v150
	v_and_b32_e32 v7, 0xffff0000, v150
	v_pk_mul_f32 v[6:7], v[12:13], v[6:7]
	s_waitcnt vmcnt(53)
	v_lshlrev_b32_e32 v2, 16, v152
	v_cvt_pk_bf16_f32 v6, v6, v7
	v_and_b32_e32 v3, 0xffff0000, v152
	ds_write_b32 v125, v6 offset:64512
	v_cvt_pk_bf16_f32 v6, v24, v25
	ds_write_b32 v114, v6 offset:3536
	v_sub_f32_e32 v6, 1.0, v2
	v_sub_f32_e32 v7, 1.0, v3
	v_mul_f32_e32 v6, v6, v12
	v_mul_f32_e32 v7, v7, v13
	v_max_f32_e32 v6, 0xda24260, v6
	v_max_f32_e32 v7, 0xda24260, v7
	v_rcp_f32_e32 v12, v6
	v_rcp_f32_e32 v13, v7
	s_waitcnt vmcnt(50)
	v_lshlrev_b32_e32 v0, 16, v155
	v_and_b32_e32 v1, 0xffff0000, v155
	v_mov_b32_e32 v168, v8
	v_pk_mul_f32 v[170:171], v[12:13], v[2:3]
	v_lshlrev_b32_e32 v2, 16, v153
	v_and_b32_e32 v3, 0xffff0000, v153
	v_pk_mul_f32 v[2:3], v[6:7], v[2:3]
	v_mov_b32_e32 v169, v24
	v_cvt_pk_bf16_f32 v2, v2, v3
	ds_write_b32 v126, v2 offset:64512
	v_cvt_pk_bf16_f32 v2, v170, v171
	ds_write_b32 v114, v2 offset:3808
	v_sub_f32_e32 v2, 1.0, v0
	v_sub_f32_e32 v3, 1.0, v1
	v_mul_f32_e32 v2, v2, v6
	v_mul_f32_e32 v3, v3, v7
	v_max_f32_e32 v2, 0xda24260, v2
	v_max_f32_e32 v172, 0xda24260, v3
	v_mov_b32_e32 v24, v9
	v_pk_mul_f32 v[6:7], v[10:11], v[2:3] op_sel_hi:[1,0]
	v_pk_mul_f32 v[8:9], v[4:5], v[172:173] op_sel_hi:[1,0]
	v_pk_mul_f32 v[10:11], v[14:15], v[172:173] op_sel_hi:[1,0]
	v_cvt_pk_bf16_f32 v8, v8, v9
	v_cvt_pk_bf16_f32 v9, v10, v11
	v_pk_mul_f32 v[10:11], v[22:23], v[172:173] op_sel_hi:[1,0]
	v_pk_mul_f32 v[14:15], v[160:161], v[172:173] op_sel_hi:[1,0]
	v_cvt_pk_bf16_f32 v10, v10, v11
	v_cvt_pk_bf16_f32 v11, v14, v15
	v_pk_mul_f32 v[14:15], v[20:21], v[172:173] op_sel_hi:[1,0]
	v_rcp_f32_e32 v20, v2
	v_rcp_f32_e32 v21, v172
	v_cvt_pk_bf16_f32 v4, v6, v7
	v_pk_mul_f32 v[6:7], v[18:19], v[2:3] op_sel_hi:[1,0]
	v_pk_mul_f32 v[12:13], v[166:167], v[2:3] op_sel_hi:[1,0]
	v_cvt_pk_bf16_f32 v5, v6, v7
	v_pk_mul_f32 v[6:7], v[26:27], v[2:3] op_sel_hi:[1,0]
	v_cvt_pk_bf16_f32 v16, v14, v15
	v_cvt_pk_bf16_f32 v6, v6, v7
	v_cvt_pk_bf16_f32 v7, v12, v13
	v_pk_mul_f32 v[12:13], v[164:165], v[2:3] op_sel_hi:[1,0]
	v_pk_mul_f32 v[14:15], v[162:163], v[2:3] op_sel_hi:[1,0]
	v_cvt_pk_bf16_f32 v12, v12, v13
	v_cvt_pk_bf16_f32 v13, v14, v15
	v_pk_mul_f32 v[14:15], v[168:169], v[2:3] op_sel_hi:[1,0]
	v_pk_mul_f32 v[0:1], v[20:21], v[0:1]
	s_waitcnt vmcnt(48)
	v_lshlrev_b32_e32 v20, 16, v156
	v_and_b32_e32 v21, 0xffff0000, v156
	v_mov_b32_e32 v3, v172
	v_pk_mul_f32 v[20:21], v[2:3], v[20:21]
	v_cvt_pk_bf16_f32 v14, v14, v15
	v_cvt_pk_bf16_f32 v15, v20, v21
	v_pk_mul_f32 v[18:19], v[158:159], v[172:173] op_sel_hi:[1,0]
	ds_write_b32 v127, v15 offset:64512
	v_cvt_pk_bf16_f32 v15, v0, v1
	v_mov_b32_e32 v20, v170
	v_mov_b32_e32 v21, v0
	v_mov_b32_e32 v0, v171
	v_cvt_pk_bf16_f32 v17, v18, v19
	v_pk_mul_f32 v[18:19], v[24:25], v[172:173] op_sel_hi:[1,0]
	v_pk_mul_f32 v[20:21], v[2:3], v[20:21] op_sel_hi:[0,1]
	v_pk_mul_f32 v[0:1], v[172:173], v[0:1] op_sel_hi:[0,1]
	v_cvt_pk_bf16_f32 v18, v18, v19
	ds_write_b32 v114, v15 offset:4080
	v_cvt_pk_bf16_f32 v15, v20, v21
	v_cvt_pk_bf16_f32 v19, v0, v1
	ds_write_b128 v128, v[4:7]
	ds_write_b128 v128, v[12:15] offset:16
	ds_write_b128 v129, v[8:11] offset:144
	ds_write_b128 v129, v[16:19] offset:160
	s_and_saveexec_b64 s[16:17], s[38:39]
	s_cbranch_execz .LBB0_259
	v_lshrrev_b32_e32 v0, 16, v151
	v_and_or_b32 v7, v154, s33, v0
	v_and_b32_e32 v0, 0xffff, v151
	v_lshl_or_b32 v11, v154, 16, v0
	v_lshrrev_b32_e32 v0, 16, v145
	v_and_or_b32 v6, v148, s33, v0
	v_and_b32_e32 v0, 0xffff, v145
	v_lshl_or_b32 v10, v148, 16, v0
	v_lshrrev_b32_e32 v0, 16, v139
	v_and_or_b32 v5, v142, s33, v0
	v_and_b32_e32 v0, 0xffff, v139
	v_lshl_or_b32 v9, v142, 16, v0
	v_lshrrev_b32_e32 v0, 16, v109
	v_and_or_b32 v4, v136, s33, v0
	v_and_b32_e32 v0, 0xffff, v109
	v_lshl_or_b32 v8, v136, 16, v0
	v_lshrrev_b32_e32 v0, 16, v89
	v_and_or_b32 v15, v94, s33, v0
	v_and_b32_e32 v0, 0xffff, v89
	v_lshl_or_b32 v19, v94, 16, v0
	v_lshrrev_b32_e32 v0, 16, v77
	v_and_or_b32 v14, v82, s33, v0
	v_and_b32_e32 v0, 0xffff, v77
	v_lshl_or_b32 v18, v82, 16, v0
	v_lshrrev_b32_e32 v0, 16, v65
	v_and_or_b32 v13, v70, s33, v0
	v_and_b32_e32 v0, 0xffff, v65
	v_lshl_or_b32 v17, v70, 16, v0
	v_lshrrev_b32_e32 v0, 16, v53
	v_and_or_b32 v12, v58, s33, v0
	v_and_b32_e32 v0, 0xffff, v53
	v_lshl_or_b32 v16, v58, 16, v0
	ds_write_b128 v130, v[16:19]
	ds_write_b128 v130, v[8:11] offset:16
	ds_write_b128 v132, v[12:15] offset:144
	ds_write_b128 v132, v[4:7] offset:160
.LBB0_259:
	s_or_b64 exec, exec, s[16:17]
	v_add_u32_e32 v0, 0x1f000, v134
	ds_write_b64 v0, v[2:3]
	ds_read_b128 v[0:3], v133
	ds_read_b128 v[4:7], v157 offset:64512
	s_cmpk_gt_u32 s18, 0x7c
	s_waitcnt lgkmcnt(0)
	v_mfma_f32_16x16x32_bf16 v[0:3], v[0:3], v[4:7], 0
	ds_read_b128 v[4:7], v133 offset:64
	ds_read_b128 v[8:11], v157 offset:64576
	s_waitcnt lgkmcnt(0)
	v_mfma_f32_16x16x32_bf16 v[0:3], v[4:7], v[8:11], v[0:3]
	ds_read_b128 v[4:7], v133 offset:128
	ds_read_b128 v[8:11], v157 offset:64640
	s_waitcnt lgkmcnt(0)
	v_mfma_f32_16x16x32_bf16 v[0:3], v[4:7], v[8:11], v[0:3]
	ds_read_b128 v[4:7], v133 offset:192
	ds_read_b128 v[8:11], v157 offset:64704
	s_waitcnt lgkmcnt(0)
	v_mfma_f32_16x16x32_bf16 v[0:3], v[4:7], v[8:11], v[0:3]
	s_nop 7
	v_cndmask_b32_e64 v0, v0, 0, s[40:41]
	v_cndmask_b32_e64 v1, 0, v1, s[42:43]
	v_cndmask_b32_e64 v2, v2, 0, s[44:45]
	v_cndmask_b32_e64 v3, v3, 0, s[46:47]
	v_cvt_pk_bf16_f32 v0, v0, v1
	v_cvt_pk_bf16_f32 v1, v2, v3
	ds_write_b64 v135, v[0:1] offset:64768
	s_cbranch_scc1 .Lh3_skipB
	v_add_u32_e32 v0, -15, v110
	v_add_u32_e32 v1, 15, v111
	v_cndmask_b32_e64 v0, v1, v0, s[36:37]
	s_and_b64 s[16:17], s[36:37], exec
	s_movk_i32 s16, 0x1000
	s_cselect_b32 s16, s16, 0xfffff000
	v_add_u32_e32 v0, s4, v0
	v_lshlrev_b32_e32 v0, 12, v0
	v_lshl_or_b32 v0, v28, 1, v0
	global_load_dword v54, v0, s[12:13]
	global_load_dword v55, v0, s[0:1]
	global_load_dword v53, v0, s[10:11]
	v_add_u32_e32 v0, s16, v0
	global_load_dword v60, v0, s[12:13]
	global_load_dword v61, v0, s[0:1]
	global_load_dword v58, v0, s[10:11]
	v_add_u32_e32 v0, s16, v0
	global_load_dword v66, v0, s[12:13]
	global_load_dword v67, v0, s[0:1]
	global_load_dword v65, v0, s[10:11]
	v_add_u32_e32 v0, s16, v0
	global_load_dword v72, v0, s[12:13]
	global_load_dword v73, v0, s[0:1]
	global_load_dword v70, v0, s[10:11]
	v_add_u32_e32 v0, s16, v0
	global_load_dword v78, v0, s[12:13]
	global_load_dword v79, v0, s[0:1]
	global_load_dword v77, v0, s[10:11]
	v_add_u32_e32 v0, s16, v0
	global_load_dword v84, v0, s[12:13]
	global_load_dword v85, v0, s[0:1]
	global_load_dword v82, v0, s[10:11]
	v_add_u32_e32 v0, s16, v0
	global_load_dword v90, v0, s[12:13]
	global_load_dword v91, v0, s[0:1]
	global_load_dword v89, v0, s[10:11]
	v_add_u32_e32 v0, s16, v0
	global_load_dword v99, v0, s[12:13]
	global_load_dword v103, v0, s[0:1]
	global_load_dword v94, v0, s[10:11]
	v_add_u32_e32 v0, s16, v0
	global_load_dword v121, v0, s[12:13]
	global_load_dword v131, v0, s[0:1]
	global_load_dword v109, v0, s[10:11]
	v_add_u32_e32 v0, s16, v0
	global_load_dword v137, v0, s[12:13]
	global_load_dword v138, v0, s[0:1]
	global_load_dword v136, v0, s[10:11]
	v_add_u32_e32 v0, s16, v0
	global_load_dword v140, v0, s[12:13]
	global_load_dword v141, v0, s[0:1]
	global_load_dword v139, v0, s[10:11]
	v_add_u32_e32 v0, s16, v0
	global_load_dword v143, v0, s[12:13]
	global_load_dword v144, v0, s[0:1]
	global_load_dword v142, v0, s[10:11]
	v_add_u32_e32 v0, s16, v0
	global_load_dword v146, v0, s[12:13]
	global_load_dword v147, v0, s[0:1]
	global_load_dword v145, v0, s[10:11]
	v_add_u32_e32 v0, s16, v0
	global_load_dword v149, v0, s[12:13]
	global_load_dword v150, v0, s[0:1]
	global_load_dword v148, v0, s[10:11]
	v_add_u32_e32 v0, s16, v0
	global_load_dword v152, v0, s[12:13]
	global_load_dword v153, v0, s[0:1]
	global_load_dword v151, v0, s[10:11]
	v_add_u32_e32 v0, s16, v0
	global_load_dword v155, v0, s[12:13]
	global_load_dword v156, v0, s[0:1]
	global_load_dword v154, v0, s[10:11]
	s_branch .LBB0_220
.Lh3_skipB:
	s_waitcnt vmcnt(0)
	s_branch .LBB0_220
